# lever 4: one static s_setprio 1 for waves 4-7 at kernel entry, all 48 per-segment priority flips of the GEMM K-loops deleted; on v093
# baseline (speedup 1.0000x reference)
; #define LAS __attribute__((address_space(3)))
; __global__ void __launch_bounds__(NWAVES * 64, 2) hymba_fwd(Args args) {
;     extern __shared__ __attribute__((aligned(16))) unsigned char lds[];
;     cg::grid_group grid = cg::this_grid();
;     Frame F;
;     F.lds = (LAS unsigned char*)lds;
;     { LAS unsigned long long* tabw = (LAS unsigned long long*)(F.lds + RING_BYTES + 1024);
;       if (threadIdx.x == 0) {
; #pragma unroll
;           for (int k = 0; k < 23; ++k) tabw[k] = (unsigned long long)args.in[k];
;           tabw[23] = (unsigned long long)args.out; tabw[24] = (unsigned long long)args.ws; }
;       F.tab = tabw; }
;     __syncthreads();
_Z9hymba_fwd4Args:
	s_load_dwordx2 s[64:65], s[0:1], 0xd0
	s_add_u32 s20, s0, 0xd0
	v_and_b32_e32 v192, 0x3ff, v0
	s_addc_u32 s21, s1, 0
	v_readfirstlane_b32 s98, v192
	s_nop 3
	s_lshr_b32 s98, s98, 6
	s_cmp_ge_u32 s98, 4
	s_cbranch_scc0 .Lprio_static_done
	s_setprio 1
.Lprio_static_done:
	v_cmp_eq_u32_e64 s[76:77], 0, v192
	s_and_saveexec_b64 s[22:23], s[76:77]
	s_cbranch_execz .LBB0_2
	s_load_dwordx16 s[4:19], s[0:1], 0x0
	s_add_i32 s3, 0, 0x20400
	s_load_dwordx16 s[40:55], s[0:1], 0x40
	v_mov_b32_e32 v1, s3
	s_add_i32 s3, 0, 0x20410
	s_waitcnt lgkmcnt(0)
	v_mov_b32_e32 v2, s4
	v_mov_b32_e32 v3, s5
	v_mov_b32_e32 v4, s6
	v_mov_b32_e32 v5, s7
	ds_write_b128 v1, v[2:5]
	v_mov_b32_e32 v2, s8
	v_mov_b32_e32 v3, s9
	v_mov_b32_e32 v4, s10
	v_mov_b32_e32 v5, s11
	v_mov_b32_e32 v1, s3
	s_add_i32 s3, 0, 0x20420
	ds_write_b128 v1, v[2:5]
	v_mov_b32_e32 v2, s12
	v_mov_b32_e32 v3, s13
	v_mov_b32_e32 v4, s14
	v_mov_b32_e32 v5, s15
	v_mov_b32_e32 v1, s3
	s_add_i32 s3, 0, 0x20430
	ds_write_b128 v1, v[2:5]
	v_mov_b32_e32 v2, s16
	v_mov_b32_e32 v3, s17
	v_mov_b32_e32 v4, s18
	v_mov_b32_e32 v5, s19
	v_mov_b32_e32 v1, s3
	s_add_i32 s3, 0, 0x20440
	s_load_dwordx16 s[4:19], s[0:1], 0x80
	ds_write_b128 v1, v[2:5]
	v_mov_b32_e32 v2, s40
	v_mov_b32_e32 v3, s41
	v_mov_b32_e32 v4, s42
	v_mov_b32_e32 v5, s43
	v_mov_b32_e32 v1, s3
	s_add_i32 s3, 0, 0x20450
	ds_write_b128 v1, v[2:5]
	v_mov_b32_e32 v2, s44
	v_mov_b32_e32 v3, s45
	v_mov_b32_e32 v4, s46
	v_mov_b32_e32 v5, s47
	v_mov_b32_e32 v1, s3
	s_add_i32 s3, 0, 0x20460
	ds_write_b128 v1, v[2:5]
	v_mov_b32_e32 v2, s48
	v_mov_b32_e32 v3, s49
	v_mov_b32_e32 v4, s50
	v_mov_b32_e32 v5, s51
	v_mov_b32_e32 v1, s3
	s_add_i32 s3, 0, 0x20470
	ds_write_b128 v1, v[2:5]
	v_mov_b32_e32 v2, s52
	v_mov_b32_e32 v3, s53
	v_mov_b32_e32 v4, s54
	v_mov_b32_e32 v5, s55
	v_mov_b32_e32 v1, s3
	ds_write_b128 v1, v[2:5]
	s_waitcnt lgkmcnt(0)
	v_mov_b32_e32 v2, s4
	v_mov_b32_e32 v3, s5
	s_add_i32 s3, 0, 0x20480
	s_load_dwordx2 s[4:5], s[0:1], 0xc0
	v_mov_b32_e32 v4, s6
	v_mov_b32_e32 v5, s7
	v_mov_b32_e32 v1, s3
	s_add_i32 s3, 0, 0x20490
	ds_write_b128 v1, v[2:5]
	v_mov_b32_e32 v2, s8
	v_mov_b32_e32 v3, s9
	v_mov_b32_e32 v4, s10
	v_mov_b32_e32 v5, s11
	v_mov_b32_e32 v1, s3
	s_add_i32 s3, 0, 0x204a0
	ds_write_b128 v1, v[2:5]
	v_mov_b32_e32 v2, s12
	v_mov_b32_e32 v3, s13
	v_mov_b32_e32 v4, s14
	v_mov_b32_e32 v5, s15
	v_mov_b32_e32 v1, s3
	s_add_i32 s3, 0, 0x204b0
	ds_write_b128 v1, v[2:5]
	v_mov_b32_e32 v2, s16
	v_mov_b32_e32 v3, s17
	v_mov_b32_e32 v4, s18
	v_mov_b32_e32 v5, s19
	v_mov_b32_e32 v1, s3
	s_add_i32 s3, 0, 0x204c0
	ds_write_b128 v1, v[2:5]
	v_mov_b32_e32 v1, s3
	s_waitcnt lgkmcnt(0)
	v_mov_b64_e32 v[2:3], s[4:5]
	ds_write_b64 v1, v[2:3]

; #define PG8_STAGE(bufoff, gbase, voff) do { _Pragma("unroll") for (int _i = 0; _i < 2; ++_i) \
;         __builtin_amdgcn_global_load_lds((const unsigned*)((const char*)(gbase) + (voff)[_i]), (PG8_LAS unsigned*)(lds + (bufoff) + ldsw + _i * 8192), 16, 0, 0); } while (0)
; #define PG8_LDA(dst, b, h) do { _Pragma("unroll") for (int m = 0; m < 4; ++m) _Pragma("unroll") for (int k = 0; k < 2; ++k) dst[m][k] = *(const PG8_LAS bf16x8*)(lds + PG8_SA(b, h) + aoff + m * 2048 + k * 1024); } while (0)
; #define PG8_MMA(ai, bj, At, Bt) do { __builtin_amdgcn_s_setprio(1); _Pragma("unroll") for (int m = 0; m < 4; ++m) _Pragma("unroll") for (int n = 0; n < 2; ++n) _Pragma("unroll") for (int k = 0; k < 2; ++k) \
;         acc[ai][bj][m][n] = __builtin_amdgcn_mfma_f32_16x16x32_bf16(Bt[n][k], At[m][k], acc[ai][bj][m][n], 0, 0, 0); __builtin_amdgcn_s_setprio(0); } while (0)
; #define PG8_WAIT_L(n) asm volatile("s_waitcnt lgkmcnt(" #n ")" ::: "memory")
; #define PG8_WAIT_V8_UNLESS(flag) asm volatile("s_cmp_lg_i32 %0, 0\n\ts_cbranch_scc1 .Lpg8rx%=\n\ts_waitcnt vmcnt(8)\n.Lpg8rx%=:" :: "s"(__builtin_amdgcn_readfirstlane(flag)) : "scc", "memory")
; #define PG8_BAR __builtin_amdgcn_s_barrier()
; #define PG8_SCHED __builtin_amdgcn_sched_barrier(0)
; template <class Epi, class Sched, bool ALIGN_EPI = false, bool SP2 = false>
; __device__ __forceinline__ void gemm_phase(PG8_LAS unsigned char* lds, const Gemm g, const Sched& S, const Epi& E) {
;     ...
;             PG8_WAIT_V8_UNLESS(rx); PG8_WAIT_L(0); PG8_BAR; PG8_MMA(0, 0, At, B0); PG8_MMA(0, 1, At, B1); PG8_BAR; PG8_SCHED;
;             PG8_STAGE(PG8_SB(0, 0), b2, voffB); PG8_STAGE(PG8_SB(0, 1), b2 + hstep, voffB); PG8_STAGE(PG8_SA(0, 0), a2, voffA); PG8_SCHED; PG8_LDA(At, 0, 1);
;             PG8_WAIT_V8_UNLESS(rx); PG8_WAIT_L(0); PG8_BAR; PG8_MMA(1, 0, At, B0); PG8_MMA(1, 1, At, B1); PG8_BAR; PG8_SCHED;
.Lpg8rx0:
	s_waitcnt lgkmcnt(0)
	s_barrier
	v_mfma_f32_16x16x32_bf16 v[124:127], v[144:147], v[178:181], v[124:127]
	v_mfma_f32_16x16x32_bf16 v[120:123], v[152:155], v[178:181], v[120:123]
	v_mfma_f32_16x16x32_bf16 v[108:111], v[144:147], v[186:189], v[108:111]
	v_mfma_f32_16x16x32_bf16 v[104:107], v[152:155], v[186:189], v[104:107]
	v_mfma_f32_16x16x32_bf16 v[92:95], v[144:147], v[208:211], v[92:95]
	v_mfma_f32_16x16x32_bf16 v[88:91], v[152:155], v[208:211], v[88:91]
	v_mfma_f32_16x16x32_bf16 v[76:79], v[144:147], v[216:219], v[76:79]
	v_mfma_f32_16x16x32_bf16 v[72:75], v[152:155], v[216:219], v[72:75]
	v_mfma_f32_16x16x32_bf16 v[124:127], v[148:151], v[182:185], v[124:127]
	v_mfma_f32_16x16x32_bf16 v[120:123], v[156:159], v[182:185], v[120:123]
	v_mfma_f32_16x16x32_bf16 v[108:111], v[148:151], v[204:207], v[108:111]
	v_mfma_f32_16x16x32_bf16 v[104:107], v[156:159], v[204:207], v[104:107]
	v_mfma_f32_16x16x32_bf16 v[92:95], v[148:151], v[212:215], v[92:95]
	v_mfma_f32_16x16x32_bf16 v[88:91], v[156:159], v[212:215], v[88:91]
	v_mfma_f32_16x16x32_bf16 v[76:79], v[148:151], v[220:223], v[76:79]
	v_mfma_f32_16x16x32_bf16 v[72:75], v[156:159], v[220:223], v[72:75]
	v_mfma_f32_16x16x32_bf16 v[116:119], v[160:163], v[178:181], v[116:119]
	v_mfma_f32_16x16x32_bf16 v[112:115], v[168:171], v[178:181], v[112:115]
	v_mfma_f32_16x16x32_bf16 v[100:103], v[160:163], v[186:189], v[100:103]
	v_mfma_f32_16x16x32_bf16 v[96:99], v[168:171], v[186:189], v[96:99]
	v_mfma_f32_16x16x32_bf16 v[84:87], v[160:163], v[208:211], v[84:87]
	v_mfma_f32_16x16x32_bf16 v[80:83], v[168:171], v[208:211], v[80:83]
	v_mfma_f32_16x16x32_bf16 v[68:71], v[160:163], v[216:219], v[68:71]
	v_mfma_f32_16x16x32_bf16 v[64:67], v[168:171], v[216:219], v[64:67]
	v_mfma_f32_16x16x32_bf16 v[116:119], v[164:167], v[182:185], v[116:119]
	v_mfma_f32_16x16x32_bf16 v[112:115], v[174:177], v[182:185], v[112:115]
	v_mfma_f32_16x16x32_bf16 v[100:103], v[164:167], v[204:207], v[100:103]
	v_mfma_f32_16x16x32_bf16 v[96:99], v[174:177], v[204:207], v[96:99]
	v_mfma_f32_16x16x32_bf16 v[84:87], v[164:167], v[212:215], v[84:87]
	v_mfma_f32_16x16x32_bf16 v[80:83], v[174:177], v[212:215], v[80:83]
	v_mfma_f32_16x16x32_bf16 v[68:71], v[164:167], v[220:223], v[68:71]
	v_mfma_f32_16x16x32_bf16 v[64:67], v[174:177], v[220:223], v[64:67]
	s_barrier
	ds_read_b128 v[178:181], v173 offset:16384
	ds_read_b128 v[182:185], v173 offset:17408
	ds_read_b128 v[186:189], v173 offset:18432
	ds_read_b128 v[204:207], v173 offset:19456
	ds_read_b128 v[208:211], v173 offset:20480
	ds_read_b128 v[212:215], v173 offset:21504
	ds_read_b128 v[216:219], v173 offset:22528
	ds_read_b128 v[220:223], v173 offset:23552
	s_add_u32 s66, s28, 0x40000
	s_addc_u32 s67, s29, 0
	s_add_i32 m0, s61, s46
	s_nop 0
	global_load_lds_dwordx4 v134, s[28:29]
	s_add_i32 m0, m0, 0x2000
	s_nop 0
	global_load_lds_dwordx4 v138, s[28:29]
	s_add_i32 m0, s65, s46
	s_nop 0
	global_load_lds_dwordx4 v134, s[66:67]
	s_add_i32 m0, m0, 0x2000
	s_nop 0
	global_load_lds_dwordx4 v138, s[66:67]
	s_mov_b32 m0, s9
	s_nop 0
	global_load_lds_dwordx4 v132, s[30:31]
	s_mov_b32 m0, s51
	s_nop 0
	global_load_lds_dwordx4 v136, s[30:31]
	s_cmp_lg_i32 s70, 0
	s_cbranch_scc1 .Lpg8rx1
	s_waitcnt vmcnt(8)
.Lpg8rx1:
	s_waitcnt lgkmcnt(0)
	s_barrier
	v_mfma_f32_16x16x32_bf16 v[60:63], v[144:147], v[178:181], v[60:63]
	v_mfma_f32_16x16x32_bf16 v[56:59], v[152:155], v[178:181], v[56:59]
	v_mfma_f32_16x16x32_bf16 v[44:47], v[144:147], v[186:189], v[44:47]
	v_mfma_f32_16x16x32_bf16 v[40:43], v[152:155], v[186:189], v[40:43]
	v_mfma_f32_16x16x32_bf16 v[28:31], v[144:147], v[208:211], v[28:31]
	v_mfma_f32_16x16x32_bf16 v[24:27], v[152:155], v[208:211], v[24:27]
	v_mfma_f32_16x16x32_bf16 v[12:15], v[144:147], v[216:219], v[12:15]
	v_mfma_f32_16x16x32_bf16 v[8:11], v[152:155], v[216:219], v[8:11]
	v_mfma_f32_16x16x32_bf16 v[60:63], v[148:151], v[182:185], v[60:63]
	v_mfma_f32_16x16x32_bf16 v[56:59], v[156:159], v[182:185], v[56:59]
	v_mfma_f32_16x16x32_bf16 v[44:47], v[148:151], v[204:207], v[44:47]
	v_mfma_f32_16x16x32_bf16 v[40:43], v[156:159], v[204:207], v[40:43]
	v_mfma_f32_16x16x32_bf16 v[28:31], v[148:151], v[212:215], v[28:31]
	v_mfma_f32_16x16x32_bf16 v[24:27], v[156:159], v[212:215], v[24:27]
	v_mfma_f32_16x16x32_bf16 v[12:15], v[148:151], v[220:223], v[12:15]
	v_mfma_f32_16x16x32_bf16 v[8:11], v[156:159], v[220:223], v[8:11]
	v_mfma_f32_16x16x32_bf16 v[52:55], v[160:163], v[178:181], v[52:55]
	v_mfma_f32_16x16x32_bf16 v[48:51], v[168:171], v[178:181], v[48:51]
	v_mfma_f32_16x16x32_bf16 v[36:39], v[160:163], v[186:189], v[36:39]
	v_mfma_f32_16x16x32_bf16 v[32:35], v[168:171], v[186:189], v[32:35]
	v_mfma_f32_16x16x32_bf16 v[20:23], v[160:163], v[208:211], v[20:23]
	v_mfma_f32_16x16x32_bf16 v[16:19], v[168:171], v[208:211], v[16:19]
	v_mfma_f32_16x16x32_bf16 v[4:7], v[160:163], v[216:219], v[4:7]
	v_mfma_f32_16x16x32_bf16 v[0:3], v[168:171], v[216:219], v[0:3]
	v_mfma_f32_16x16x32_bf16 v[52:55], v[164:167], v[182:185], v[52:55]
	v_mfma_f32_16x16x32_bf16 v[48:51], v[174:177], v[182:185], v[48:51]
	v_mfma_f32_16x16x32_bf16 v[36:39], v[164:167], v[204:207], v[36:39]
	v_mfma_f32_16x16x32_bf16 v[32:35], v[174:177], v[204:207], v[32:35]
	v_mfma_f32_16x16x32_bf16 v[20:23], v[164:167], v[212:215], v[20:23]
	v_mfma_f32_16x16x32_bf16 v[16:19], v[174:177], v[212:215], v[16:19]
	v_mfma_f32_16x16x32_bf16 v[4:7], v[164:167], v[220:223], v[4:7]
	v_mfma_f32_16x16x32_bf16 v[0:3], v[174:177], v[220:223], v[0:3]
	s_barrier
; #define PG8_STAGE(bufoff, gbase, voff) do { _Pragma("unroll") for (int _i = 0; _i < 2; ++_i) \
;         __builtin_amdgcn_global_load_lds((const unsigned*)((const char*)(gbase) + (voff)[_i]), (PG8_LAS unsigned*)(lds + (bufoff) + ldsw + _i * 8192), 16, 0, 0); } while (0)
; #define PG8_LDA(dst, b, h) do { _Pragma("unroll") for (int m = 0; m < 4; ++m) _Pragma("unroll") for (int k = 0; k < 2; ++k) dst[m][k] = *(const PG8_LAS bf16x8*)(lds + PG8_SA(b, h) + aoff + m * 2048 + k * 1024); } while (0)
; #define PG8_LDB(dst, b, h) do { _Pragma("unroll") for (int n = 0; n < 2; ++n) _Pragma("unroll") for (int k = 0; k < 2; ++k) dst[n][k] = *(const PG8_LAS bf16x8*)(lds + PG8_SB(b, h) + boff + n * 2048 + k * 1024); } while (0)
; #define PG8_MMA(ai, bj, At, Bt) do { __builtin_amdgcn_s_setprio(1); _Pragma("unroll") for (int m = 0; m < 4; ++m) _Pragma("unroll") for (int n = 0; n < 2; ++n) _Pragma("unroll") for (int k = 0; k < 2; ++k) \
;         acc[ai][bj][m][n] = __builtin_amdgcn_mfma_f32_16x16x32_bf16(Bt[n][k], At[m][k], acc[ai][bj][m][n], 0, 0, 0); __builtin_amdgcn_s_setprio(0); } while (0)
; #define PG8_WAIT_V(n) asm volatile("s_waitcnt vmcnt(" #n ")" ::: "memory")
; #define PG8_WAIT_L(n) asm volatile("s_waitcnt lgkmcnt(" #n ")" ::: "memory")
; #define PG8_BAR __builtin_amdgcn_s_barrier()
; #define PG8_SCHED __builtin_amdgcn_sched_barrier(0)
; template <class Epi, class Sched, bool ALIGN_EPI = false, bool SP2 = false>
; __device__ __forceinline__ void gemm_phase(PG8_LAS unsigned char* lds, const Gemm g, const Sched& S, const Epi& E) {
;     ...
;         for (int t = 0; t < nt; t += 2) {
;     ...
;             PG8_STAGE(PG8_SA(0, 1), a2 + hstep, voffA); PG8_SCHED; PG8_LDB(B0, 1, 0); PG8_LDB(B1, 1, 1); PG8_SCHED; PG8_LDA(At, 1, 0);
;             PG8_WAIT_V(8); PG8_WAIT_L(0); PG8_BAR; PG8_MMA(0, 0, At, B0); PG8_MMA(0, 1, At, B1); PG8_BAR; PG8_SCHED;
;             PG8_STAGE(PG8_SB(1, 0), b3, voffB); PG8_STAGE(PG8_SB(1, 1), b3 + hstep, voffB); PG8_STAGE(PG8_SA(1, 0), a3, voffA); PG8_SCHED; PG8_LDA(At, 1, 1);
;             PG8_WAIT_V(8); PG8_WAIT_L(0); PG8_BAR; PG8_MMA(1, 0, At, B0); PG8_MMA(1, 1, At, B1); PG8_BAR; PG8_SCHED;
	s_mov_b64 s[98:99], s[30:31]
	s_add_u32 s100, s30, 0x40000
	s_addc_u32 s101, s31, 0
	s_add_i32 s30, 0, 0x18000
	s_add_i32 s31, 0, 0x1c000
	v_add_u32_e32 v156, s30, v172
	v_add_u32_e32 v174, s31, v172
	ds_read_b128 v[144:147], v156
	ds_read_b128 v[148:151], v156 offset:1024
	ds_read_b128 v[152:155], v156 offset:2048
	ds_read_b128 v[156:159], v156 offset:3072
	ds_read_b128 v[160:163], v174
	ds_read_b128 v[164:167], v174 offset:1024
	ds_read_b128 v[168:171], v174 offset:2048
	ds_read_b128 v[174:177], v174 offset:3072
	ds_read_b128 v[178:181], v173 offset:32768
	ds_read_b128 v[182:185], v173 offset:33792
	ds_read_b128 v[186:189], v173 offset:34816
	ds_read_b128 v[204:207], v173 offset:35840
	ds_read_b128 v[208:211], v173 offset:36864
	ds_read_b128 v[212:215], v173 offset:37888
	ds_read_b128 v[216:219], v173 offset:38912
	ds_read_b128 v[220:223], v173 offset:39936
	s_mov_b32 m0, s52
	s_nop 0
	global_load_lds_dwordx4 v132, s[100:101]
	s_mov_b32 m0, s53
	s_nop 0
	global_load_lds_dwordx4 v136, s[100:101]
	s_waitcnt vmcnt(8)
	s_waitcnt lgkmcnt(0)
	s_barrier
	v_mfma_f32_16x16x32_bf16 v[124:127], v[144:147], v[178:181], v[124:127]
	v_mfma_f32_16x16x32_bf16 v[120:123], v[152:155], v[178:181], v[120:123]
	v_mfma_f32_16x16x32_bf16 v[108:111], v[144:147], v[186:189], v[108:111]
	v_mfma_f32_16x16x32_bf16 v[104:107], v[152:155], v[186:189], v[104:107]
	v_mfma_f32_16x16x32_bf16 v[92:95], v[144:147], v[208:211], v[92:95]
	v_mfma_f32_16x16x32_bf16 v[88:91], v[152:155], v[208:211], v[88:91]
	v_mfma_f32_16x16x32_bf16 v[76:79], v[144:147], v[216:219], v[76:79]
	v_mfma_f32_16x16x32_bf16 v[72:75], v[152:155], v[216:219], v[72:75]
	v_mfma_f32_16x16x32_bf16 v[124:127], v[148:151], v[182:185], v[124:127]
	v_mfma_f32_16x16x32_bf16 v[120:123], v[156:159], v[182:185], v[120:123]
	v_mfma_f32_16x16x32_bf16 v[108:111], v[148:151], v[204:207], v[108:111]
	v_mfma_f32_16x16x32_bf16 v[104:107], v[156:159], v[204:207], v[104:107]
	v_mfma_f32_16x16x32_bf16 v[92:95], v[148:151], v[212:215], v[92:95]
	v_mfma_f32_16x16x32_bf16 v[88:91], v[156:159], v[212:215], v[88:91]
	v_mfma_f32_16x16x32_bf16 v[76:79], v[148:151], v[220:223], v[76:79]
	v_mfma_f32_16x16x32_bf16 v[72:75], v[156:159], v[220:223], v[72:75]
	v_mfma_f32_16x16x32_bf16 v[116:119], v[160:163], v[178:181], v[116:119]
	v_mfma_f32_16x16x32_bf16 v[112:115], v[168:171], v[178:181], v[112:115]
	v_mfma_f32_16x16x32_bf16 v[100:103], v[160:163], v[186:189], v[100:103]
	v_mfma_f32_16x16x32_bf16 v[96:99], v[168:171], v[186:189], v[96:99]
	v_mfma_f32_16x16x32_bf16 v[84:87], v[160:163], v[208:211], v[84:87]
	v_mfma_f32_16x16x32_bf16 v[80:83], v[168:171], v[208:211], v[80:83]
	v_mfma_f32_16x16x32_bf16 v[68:71], v[160:163], v[216:219], v[68:71]
	v_mfma_f32_16x16x32_bf16 v[64:67], v[168:171], v[216:219], v[64:67]
	v_mfma_f32_16x16x32_bf16 v[116:119], v[164:167], v[182:185], v[116:119]
	v_mfma_f32_16x16x32_bf16 v[112:115], v[174:177], v[182:185], v[112:115]
	v_mfma_f32_16x16x32_bf16 v[100:103], v[164:167], v[204:207], v[100:103]
	v_mfma_f32_16x16x32_bf16 v[96:99], v[174:177], v[204:207], v[96:99]
	v_mfma_f32_16x16x32_bf16 v[84:87], v[164:167], v[212:215], v[84:87]
	v_mfma_f32_16x16x32_bf16 v[80:83], v[174:177], v[212:215], v[80:83]
	v_mfma_f32_16x16x32_bf16 v[68:71], v[164:167], v[220:223], v[68:71]
	v_mfma_f32_16x16x32_bf16 v[64:67], v[174:177], v[220:223], v[64:67]
	s_barrier
	ds_read_b128 v[178:181], v173 offset:49152
	ds_read_b128 v[182:185], v173 offset:50176
	ds_read_b128 v[186:189], v173 offset:51200
	ds_read_b128 v[204:207], v173 offset:52224
	ds_read_b128 v[208:211], v173 offset:53248
	ds_read_b128 v[212:215], v173 offset:54272
	ds_read_b128 v[216:219], v173 offset:55296
	ds_read_b128 v[220:223], v173 offset:56320
	s_add_u32 s100, s28, 0x80
	s_addc_u32 s101, s29, 0
	s_add_u32 s28, s28, 0x40080
	s_addc_u32 s29, s29, 0
	s_add_u32 s98, s98, 0x80
	s_addc_u32 s99, s99, 0
	s_add_i32 m0, s30, s46
	s_nop 0
	global_load_lds_dwordx4 v134, s[100:101]
	s_add_i32 m0, m0, 0x2000
	s_nop 0
	global_load_lds_dwordx4 v138, s[100:101]
	s_add_i32 m0, s31, s46
	s_nop 0
	global_load_lds_dwordx4 v134, s[28:29]
	s_add_i32 m0, m0, 0x2000
	s_nop 0
	global_load_lds_dwordx4 v138, s[28:29]
	s_mov_b32 m0, s54
	s_nop 0
	global_load_lds_dwordx4 v132, s[98:99]
	s_mov_b32 m0, s55
	s_nop 0
	global_load_lds_dwordx4 v136, s[98:99]
	s_waitcnt vmcnt(8)
	s_waitcnt lgkmcnt(0)
	s_barrier
	v_mfma_f32_16x16x32_bf16 v[60:63], v[144:147], v[178:181], v[60:63]
	v_mfma_f32_16x16x32_bf16 v[56:59], v[152:155], v[178:181], v[56:59]
	v_mfma_f32_16x16x32_bf16 v[44:47], v[144:147], v[186:189], v[44:47]
	v_mfma_f32_16x16x32_bf16 v[40:43], v[152:155], v[186:189], v[40:43]
	v_mfma_f32_16x16x32_bf16 v[28:31], v[144:147], v[208:211], v[28:31]
	v_mfma_f32_16x16x32_bf16 v[24:27], v[152:155], v[208:211], v[24:27]
	v_mfma_f32_16x16x32_bf16 v[12:15], v[144:147], v[216:219], v[12:15]
	v_mfma_f32_16x16x32_bf16 v[8:11], v[152:155], v[216:219], v[8:11]
	v_mfma_f32_16x16x32_bf16 v[60:63], v[148:151], v[182:185], v[60:63]
	v_mfma_f32_16x16x32_bf16 v[56:59], v[156:159], v[182:185], v[56:59]
	v_mfma_f32_16x16x32_bf16 v[44:47], v[148:151], v[204:207], v[44:47]
	v_mfma_f32_16x16x32_bf16 v[40:43], v[156:159], v[204:207], v[40:43]
	v_mfma_f32_16x16x32_bf16 v[28:31], v[148:151], v[212:215], v[28:31]
	v_mfma_f32_16x16x32_bf16 v[24:27], v[156:159], v[212:215], v[24:27]
	v_mfma_f32_16x16x32_bf16 v[12:15], v[148:151], v[220:223], v[12:15]
	v_mfma_f32_16x16x32_bf16 v[8:11], v[156:159], v[220:223], v[8:11]
	v_mfma_f32_16x16x32_bf16 v[52:55], v[160:163], v[178:181], v[52:55]
	v_mfma_f32_16x16x32_bf16 v[48:51], v[168:171], v[178:181], v[48:51]
	v_mfma_f32_16x16x32_bf16 v[36:39], v[160:163], v[186:189], v[36:39]
	v_mfma_f32_16x16x32_bf16 v[32:35], v[168:171], v[186:189], v[32:35]
	v_mfma_f32_16x16x32_bf16 v[20:23], v[160:163], v[208:211], v[20:23]
	v_mfma_f32_16x16x32_bf16 v[16:19], v[168:171], v[208:211], v[16:19]
	v_mfma_f32_16x16x32_bf16 v[4:7], v[160:163], v[216:219], v[4:7]
	v_mfma_f32_16x16x32_bf16 v[0:3], v[168:171], v[216:219], v[0:3]
	v_mfma_f32_16x16x32_bf16 v[52:55], v[164:167], v[182:185], v[52:55]
	v_mfma_f32_16x16x32_bf16 v[48:51], v[174:177], v[182:185], v[48:51]
	v_mfma_f32_16x16x32_bf16 v[36:39], v[164:167], v[204:207], v[36:39]
	v_mfma_f32_16x16x32_bf16 v[32:35], v[174:177], v[204:207], v[32:35]
	v_mfma_f32_16x16x32_bf16 v[20:23], v[164:167], v[212:215], v[20:23]
	v_mfma_f32_16x16x32_bf16 v[16:19], v[174:177], v[212:215], v[16:19]
	v_mfma_f32_16x16x32_bf16 v[4:7], v[164:167], v[220:223], v[4:7]
	v_mfma_f32_16x16x32_bf16 v[0:3], v[174:177], v[220:223], v[0:3]
	s_barrier
	s_add_i32 s60, s60, 2
	s_add_u32 vcc_lo, vcc_lo, 0x100
	s_addc_u32 vcc_hi, vcc_hi, 0
	s_cmp_gt_u32 s60, 13
	s_cbranch_scc0 .LBB0_148
	s_and_b64 vcc, exec, s[62:63]
	s_cbranch_vccz .LBB0_151
	s_barrier

; #define PG8_STAGE(bufoff, gbase, voff) do { _Pragma("unroll") for (int _i = 0; _i < 2; ++_i) \
;         __builtin_amdgcn_global_load_lds((const unsigned*)((const char*)(gbase) + (voff)[_i]), (PG8_LAS unsigned*)(lds + (bufoff) + ldsw + _i * 8192), 16, 0, 0); } while (0)
; #define PG8_LDA(dst, b, h) do { _Pragma("unroll") for (int m = 0; m < 4; ++m) _Pragma("unroll") for (int k = 0; k < 2; ++k) dst[m][k] = *(const PG8_LAS bf16x8*)(lds + PG8_SA(b, h) + aoff + m * 2048 + k * 1024); } while (0)
; #define PG8_MMA(ai, bj, At, Bt) do { __builtin_amdgcn_s_setprio(1); _Pragma("unroll") for (int m = 0; m < 4; ++m) _Pragma("unroll") for (int n = 0; n < 2; ++n) _Pragma("unroll") for (int k = 0; k < 2; ++k) \
;         acc[ai][bj][m][n] = __builtin_amdgcn_mfma_f32_16x16x32_bf16(Bt[n][k], At[m][k], acc[ai][bj][m][n], 0, 0, 0); __builtin_amdgcn_s_setprio(0); } while (0)
; #define PG8_WAIT_L(n) asm volatile("s_waitcnt lgkmcnt(" #n ")" ::: "memory")
; #define PG8_WAIT_V8_UNLESS(flag) asm volatile("s_cmp_lg_i32 %0, 0\n\ts_cbranch_scc1 .Lpg8rx%=\n\ts_waitcnt vmcnt(8)\n.Lpg8rx%=:" :: "s"(__builtin_amdgcn_readfirstlane(flag)) : "scc", "memory")
; #define PG8_BAR __builtin_amdgcn_s_barrier()
; #define PG8_SCHED __builtin_amdgcn_sched_barrier(0)
; template <class Epi, class Sched, bool ALIGN_EPI = false, bool SP2 = false>
; __device__ __forceinline__ void gemm_phase(PG8_LAS unsigned char* lds, const Gemm g, const Sched& S, const Epi& E) {
;     ...
;             PG8_WAIT_V8_UNLESS(rx); PG8_WAIT_L(0); PG8_BAR; PG8_MMA(0, 0, At, B0); PG8_MMA(0, 1, At, B1); PG8_BAR; PG8_SCHED;
;             PG8_STAGE(PG8_SB(0, 0), b2, voffB); PG8_STAGE(PG8_SB(0, 1), b2 + hstep, voffB); PG8_STAGE(PG8_SA(0, 0), a2, voffA); PG8_SCHED; PG8_LDA(At, 0, 1);
;             PG8_WAIT_V8_UNLESS(rx); PG8_WAIT_L(0); PG8_BAR; PG8_MMA(1, 0, At, B0); PG8_MMA(1, 1, At, B1); PG8_BAR; PG8_SCHED;
.Lpg8rx2:
	s_waitcnt lgkmcnt(0)
	s_barrier
	v_mfma_f32_16x16x32_bf16 v[152:155], v[120:123], v[164:167], v[152:155]
	v_mfma_f32_16x16x32_bf16 v[148:151], v[132:135], v[164:167], v[148:151]
	v_mfma_f32_16x16x32_bf16 v[108:111], v[120:123], v[172:175], v[108:111]
	v_mfma_f32_16x16x32_bf16 v[104:107], v[132:135], v[172:175], v[104:107]
	v_mfma_f32_16x16x32_bf16 v[92:95], v[120:123], v[180:183], v[92:95]
	v_mfma_f32_16x16x32_bf16 v[88:91], v[132:135], v[180:183], v[88:91]
	v_mfma_f32_16x16x32_bf16 v[76:79], v[120:123], v[188:191], v[76:79]
	v_mfma_f32_16x16x32_bf16 v[72:75], v[132:135], v[188:191], v[72:75]
	v_mfma_f32_16x16x32_bf16 v[152:155], v[128:131], v[168:171], v[152:155]
	v_mfma_f32_16x16x32_bf16 v[148:151], v[136:139], v[168:171], v[148:151]
	v_mfma_f32_16x16x32_bf16 v[108:111], v[128:131], v[176:179], v[108:111]
	v_mfma_f32_16x16x32_bf16 v[104:107], v[136:139], v[176:179], v[104:107]
	v_mfma_f32_16x16x32_bf16 v[92:95], v[128:131], v[184:187], v[92:95]
	v_mfma_f32_16x16x32_bf16 v[88:91], v[136:139], v[184:187], v[88:91]
	v_mfma_f32_16x16x32_bf16 v[76:79], v[128:131], v[214:217], v[76:79]
	v_mfma_f32_16x16x32_bf16 v[72:75], v[136:139], v[214:217], v[72:75]
	v_mfma_f32_16x16x32_bf16 v[124:127], v[140:143], v[164:167], v[124:127]
	v_mfma_f32_16x16x32_bf16 v[112:115], v[156:159], v[164:167], v[112:115]
	v_mfma_f32_16x16x32_bf16 v[100:103], v[140:143], v[172:175], v[100:103]
	v_mfma_f32_16x16x32_bf16 v[96:99], v[156:159], v[172:175], v[96:99]
	v_mfma_f32_16x16x32_bf16 v[84:87], v[140:143], v[180:183], v[84:87]
	v_mfma_f32_16x16x32_bf16 v[80:83], v[156:159], v[180:183], v[80:83]
	v_mfma_f32_16x16x32_bf16 v[68:71], v[140:143], v[188:191], v[68:71]
	v_mfma_f32_16x16x32_bf16 v[64:67], v[156:159], v[188:191], v[64:67]
	v_mfma_f32_16x16x32_bf16 v[124:127], v[144:147], v[168:171], v[124:127]
	v_mfma_f32_16x16x32_bf16 v[112:115], v[160:163], v[168:171], v[112:115]
	v_mfma_f32_16x16x32_bf16 v[100:103], v[144:147], v[176:179], v[100:103]
	v_mfma_f32_16x16x32_bf16 v[96:99], v[160:163], v[176:179], v[96:99]
	v_mfma_f32_16x16x32_bf16 v[84:87], v[144:147], v[184:187], v[84:87]
	v_mfma_f32_16x16x32_bf16 v[80:83], v[160:163], v[184:187], v[80:83]
	v_mfma_f32_16x16x32_bf16 v[68:71], v[144:147], v[214:217], v[68:71]
	v_mfma_f32_16x16x32_bf16 v[64:67], v[160:163], v[214:217], v[64:67]
	s_barrier
	ds_read_b128 v[164:167], v248 offset:16384
	ds_read_b128 v[168:171], v248 offset:17408
	ds_read_b128 v[172:175], v248 offset:18432
	ds_read_b128 v[176:179], v248 offset:19456
	ds_read_b128 v[180:183], v248 offset:20480
	ds_read_b128 v[184:187], v248 offset:21504
	ds_read_b128 v[188:191], v248 offset:22528
	ds_read_b128 v[214:217], v248 offset:23552
	s_add_u32 s60, s28, 0x40000
	s_addc_u32 s61, s29, 0
	s_add_i32 m0, s59, s39
	s_nop 0
	global_load_lds_dwordx4 v194, s[28:29]
	s_add_i32 m0, m0, 0x2000
	s_nop 0
	global_load_lds_dwordx4 v208, s[28:29]
	s_add_i32 m0, s65, s39
	s_nop 0
	global_load_lds_dwordx4 v194, s[60:61]
	s_add_i32 m0, m0, 0x2000
	s_nop 0
	global_load_lds_dwordx4 v208, s[60:61]
	s_mov_b32 m0, s41
	s_nop 0
	global_load_lds_dwordx4 v204, s[30:31]
	s_mov_b32 m0, s44
	s_nop 0
	global_load_lds_dwordx4 v206, s[30:31]
	s_cmp_lg_i32 s66, 0
	s_cbranch_scc1 .Lpg8rx3
	s_waitcnt vmcnt(8)
.Lpg8rx3:
	s_waitcnt lgkmcnt(0)
	s_barrier
	v_mfma_f32_16x16x32_bf16 v[60:63], v[120:123], v[164:167], v[60:63]
	v_mfma_f32_16x16x32_bf16 v[56:59], v[132:135], v[164:167], v[56:59]
	v_mfma_f32_16x16x32_bf16 v[44:47], v[120:123], v[172:175], v[44:47]
	v_mfma_f32_16x16x32_bf16 v[40:43], v[132:135], v[172:175], v[40:43]
	v_mfma_f32_16x16x32_bf16 v[28:31], v[120:123], v[180:183], v[28:31]
	v_mfma_f32_16x16x32_bf16 v[24:27], v[132:135], v[180:183], v[24:27]
	v_mfma_f32_16x16x32_bf16 v[12:15], v[120:123], v[188:191], v[12:15]
	v_mfma_f32_16x16x32_bf16 v[8:11], v[132:135], v[188:191], v[8:11]
	v_mfma_f32_16x16x32_bf16 v[60:63], v[128:131], v[168:171], v[60:63]
	v_mfma_f32_16x16x32_bf16 v[56:59], v[136:139], v[168:171], v[56:59]
	v_mfma_f32_16x16x32_bf16 v[44:47], v[128:131], v[176:179], v[44:47]
	v_mfma_f32_16x16x32_bf16 v[40:43], v[136:139], v[176:179], v[40:43]
	v_mfma_f32_16x16x32_bf16 v[28:31], v[128:131], v[184:187], v[28:31]
	v_mfma_f32_16x16x32_bf16 v[24:27], v[136:139], v[184:187], v[24:27]
	v_mfma_f32_16x16x32_bf16 v[12:15], v[128:131], v[214:217], v[12:15]
	v_mfma_f32_16x16x32_bf16 v[8:11], v[136:139], v[214:217], v[8:11]
	v_mfma_f32_16x16x32_bf16 v[52:55], v[140:143], v[164:167], v[52:55]
	v_mfma_f32_16x16x32_bf16 v[48:51], v[156:159], v[164:167], v[48:51]
	v_mfma_f32_16x16x32_bf16 v[36:39], v[140:143], v[172:175], v[36:39]
	v_mfma_f32_16x16x32_bf16 v[32:35], v[156:159], v[172:175], v[32:35]
	v_mfma_f32_16x16x32_bf16 v[20:23], v[140:143], v[180:183], v[20:23]
	v_mfma_f32_16x16x32_bf16 v[16:19], v[156:159], v[180:183], v[16:19]
	v_mfma_f32_16x16x32_bf16 v[4:7], v[140:143], v[188:191], v[4:7]
	v_mfma_f32_16x16x32_bf16 v[0:3], v[156:159], v[188:191], v[0:3]
	v_mfma_f32_16x16x32_bf16 v[52:55], v[144:147], v[168:171], v[52:55]
	v_mfma_f32_16x16x32_bf16 v[48:51], v[160:163], v[168:171], v[48:51]
	v_mfma_f32_16x16x32_bf16 v[36:39], v[144:147], v[176:179], v[36:39]
	v_mfma_f32_16x16x32_bf16 v[32:35], v[160:163], v[176:179], v[32:35]
	v_mfma_f32_16x16x32_bf16 v[20:23], v[144:147], v[184:187], v[20:23]
	v_mfma_f32_16x16x32_bf16 v[16:19], v[160:163], v[184:187], v[16:19]
	v_mfma_f32_16x16x32_bf16 v[4:7], v[144:147], v[214:217], v[4:7]
	v_mfma_f32_16x16x32_bf16 v[0:3], v[160:163], v[214:217], v[0:3]
	s_barrier
; #define PG8_STAGE(bufoff, gbase, voff) do { _Pragma("unroll") for (int _i = 0; _i < 2; ++_i) \
;         __builtin_amdgcn_global_load_lds((const unsigned*)((const char*)(gbase) + (voff)[_i]), (PG8_LAS unsigned*)(lds + (bufoff) + ldsw + _i * 8192), 16, 0, 0); } while (0)
; #define PG8_LDA(dst, b, h) do { _Pragma("unroll") for (int m = 0; m < 4; ++m) _Pragma("unroll") for (int k = 0; k < 2; ++k) dst[m][k] = *(const PG8_LAS bf16x8*)(lds + PG8_SA(b, h) + aoff + m * 2048 + k * 1024); } while (0)
; #define PG8_LDB(dst, b, h) do { _Pragma("unroll") for (int n = 0; n < 2; ++n) _Pragma("unroll") for (int k = 0; k < 2; ++k) dst[n][k] = *(const PG8_LAS bf16x8*)(lds + PG8_SB(b, h) + boff + n * 2048 + k * 1024); } while (0)
; #define PG8_MMA(ai, bj, At, Bt) do { __builtin_amdgcn_s_setprio(1); _Pragma("unroll") for (int m = 0; m < 4; ++m) _Pragma("unroll") for (int n = 0; n < 2; ++n) _Pragma("unroll") for (int k = 0; k < 2; ++k) \
;         acc[ai][bj][m][n] = __builtin_amdgcn_mfma_f32_16x16x32_bf16(Bt[n][k], At[m][k], acc[ai][bj][m][n], 0, 0, 0); __builtin_amdgcn_s_setprio(0); } while (0)
; #define PG8_WAIT_V(n) asm volatile("s_waitcnt vmcnt(" #n ")" ::: "memory")
; #define PG8_WAIT_L(n) asm volatile("s_waitcnt lgkmcnt(" #n ")" ::: "memory")
; #define PG8_BAR __builtin_amdgcn_s_barrier()
; #define PG8_SCHED __builtin_amdgcn_sched_barrier(0)
; template <class Epi, class Sched, bool ALIGN_EPI = false, bool SP2 = false>
; __device__ __forceinline__ void gemm_phase(PG8_LAS unsigned char* lds, const Gemm g, const Sched& S, const Epi& E) {
;     ...
;         for (int t = 0; t < nt; t += 2) {
;     ...
;             PG8_STAGE(PG8_SA(0, 1), a2 + hstep, voffA); PG8_SCHED; PG8_LDB(B0, 1, 0); PG8_LDB(B1, 1, 1); PG8_SCHED; PG8_LDA(At, 1, 0);
;             PG8_WAIT_V(8); PG8_WAIT_L(0); PG8_BAR; PG8_MMA(0, 0, At, B0); PG8_MMA(0, 1, At, B1); PG8_BAR; PG8_SCHED;
;             PG8_STAGE(PG8_SB(1, 0), b3, voffB); PG8_STAGE(PG8_SB(1, 1), b3 + hstep, voffB); PG8_STAGE(PG8_SA(1, 0), a3, voffA); PG8_SCHED; PG8_LDA(At, 1, 1);
;             PG8_WAIT_V(8); PG8_WAIT_L(0); PG8_BAR; PG8_MMA(1, 0, At, B0); PG8_MMA(1, 1, At, B1); PG8_BAR; PG8_SCHED;
	s_mov_b64 s[98:99], s[30:31]
	s_add_u32 s100, s30, 0x40000
	s_addc_u32 s101, s31, 0
	s_add_i32 s30, 0, 0x18000
	s_add_i32 s31, 0, 0x1c000
	v_add_u32_e32 v136, s30, v247
	v_add_u32_e32 v160, s31, v247
	ds_read_b128 v[120:123], v136
	ds_read_b128 v[128:131], v136 offset:1024
	ds_read_b128 v[132:135], v136 offset:2048
	ds_read_b128 v[136:139], v136 offset:3072
	ds_read_b128 v[140:143], v160
	ds_read_b128 v[144:147], v160 offset:1024
	ds_read_b128 v[156:159], v160 offset:2048
	ds_read_b128 v[160:163], v160 offset:3072
	ds_read_b128 v[164:167], v248 offset:32768
	ds_read_b128 v[168:171], v248 offset:33792
	ds_read_b128 v[172:175], v248 offset:34816
	ds_read_b128 v[176:179], v248 offset:35840
	ds_read_b128 v[180:183], v248 offset:36864
	ds_read_b128 v[184:187], v248 offset:37888
	ds_read_b128 v[188:191], v248 offset:38912
	ds_read_b128 v[214:217], v248 offset:39936
	s_mov_b32 m0, s46
	s_nop 0
	global_load_lds_dwordx4 v204, s[100:101]
	s_mov_b32 m0, s48
	s_nop 0
	global_load_lds_dwordx4 v206, s[100:101]
	s_waitcnt vmcnt(8)
	s_waitcnt lgkmcnt(0)
	s_barrier
	v_mfma_f32_16x16x32_bf16 v[152:155], v[120:123], v[164:167], v[152:155]
	v_mfma_f32_16x16x32_bf16 v[148:151], v[132:135], v[164:167], v[148:151]
	v_mfma_f32_16x16x32_bf16 v[108:111], v[120:123], v[172:175], v[108:111]
	v_mfma_f32_16x16x32_bf16 v[104:107], v[132:135], v[172:175], v[104:107]
	v_mfma_f32_16x16x32_bf16 v[92:95], v[120:123], v[180:183], v[92:95]
	v_mfma_f32_16x16x32_bf16 v[88:91], v[132:135], v[180:183], v[88:91]
	v_mfma_f32_16x16x32_bf16 v[76:79], v[120:123], v[188:191], v[76:79]
	v_mfma_f32_16x16x32_bf16 v[72:75], v[132:135], v[188:191], v[72:75]
	v_mfma_f32_16x16x32_bf16 v[152:155], v[128:131], v[168:171], v[152:155]
	v_mfma_f32_16x16x32_bf16 v[148:151], v[136:139], v[168:171], v[148:151]
	v_mfma_f32_16x16x32_bf16 v[108:111], v[128:131], v[176:179], v[108:111]
	v_mfma_f32_16x16x32_bf16 v[104:107], v[136:139], v[176:179], v[104:107]
	v_mfma_f32_16x16x32_bf16 v[92:95], v[128:131], v[184:187], v[92:95]
	v_mfma_f32_16x16x32_bf16 v[88:91], v[136:139], v[184:187], v[88:91]
	v_mfma_f32_16x16x32_bf16 v[76:79], v[128:131], v[214:217], v[76:79]
	v_mfma_f32_16x16x32_bf16 v[72:75], v[136:139], v[214:217], v[72:75]
	v_mfma_f32_16x16x32_bf16 v[124:127], v[140:143], v[164:167], v[124:127]
	v_mfma_f32_16x16x32_bf16 v[112:115], v[156:159], v[164:167], v[112:115]
	v_mfma_f32_16x16x32_bf16 v[100:103], v[140:143], v[172:175], v[100:103]
	v_mfma_f32_16x16x32_bf16 v[96:99], v[156:159], v[172:175], v[96:99]
	v_mfma_f32_16x16x32_bf16 v[84:87], v[140:143], v[180:183], v[84:87]
	v_mfma_f32_16x16x32_bf16 v[80:83], v[156:159], v[180:183], v[80:83]
	v_mfma_f32_16x16x32_bf16 v[68:71], v[140:143], v[188:191], v[68:71]
	v_mfma_f32_16x16x32_bf16 v[64:67], v[156:159], v[188:191], v[64:67]
	v_mfma_f32_16x16x32_bf16 v[124:127], v[144:147], v[168:171], v[124:127]
	v_mfma_f32_16x16x32_bf16 v[112:115], v[160:163], v[168:171], v[112:115]
	v_mfma_f32_16x16x32_bf16 v[100:103], v[144:147], v[176:179], v[100:103]
	v_mfma_f32_16x16x32_bf16 v[96:99], v[160:163], v[176:179], v[96:99]
	v_mfma_f32_16x16x32_bf16 v[84:87], v[144:147], v[184:187], v[84:87]
	v_mfma_f32_16x16x32_bf16 v[80:83], v[160:163], v[184:187], v[80:83]
	v_mfma_f32_16x16x32_bf16 v[68:71], v[144:147], v[214:217], v[68:71]
	v_mfma_f32_16x16x32_bf16 v[64:67], v[160:163], v[214:217], v[64:67]
	s_barrier
	ds_read_b128 v[164:167], v248 offset:49152
	ds_read_b128 v[168:171], v248 offset:50176
	ds_read_b128 v[172:175], v248 offset:51200
	ds_read_b128 v[176:179], v248 offset:52224
	ds_read_b128 v[180:183], v248 offset:53248
	ds_read_b128 v[184:187], v248 offset:54272
	ds_read_b128 v[188:191], v248 offset:55296
	ds_read_b128 v[214:217], v248 offset:56320
	s_add_u32 s100, s28, 0x80
	s_addc_u32 s101, s29, 0
	s_add_u32 s28, s28, 0x40080
	s_addc_u32 s29, s29, 0
	s_add_u32 s98, s98, 0x80
	s_addc_u32 s99, s99, 0
	s_add_i32 m0, s30, s39
	s_nop 0
	global_load_lds_dwordx4 v194, s[100:101]
	s_add_i32 m0, m0, 0x2000
	s_nop 0
	global_load_lds_dwordx4 v208, s[100:101]
	s_add_i32 m0, s31, s39
	s_nop 0
	global_load_lds_dwordx4 v194, s[28:29]
	s_add_i32 m0, m0, 0x2000
	s_nop 0
	global_load_lds_dwordx4 v208, s[28:29]
	s_mov_b32 m0, s50
	s_nop 0
	global_load_lds_dwordx4 v204, s[98:99]
	s_mov_b32 m0, s51
	s_nop 0
	global_load_lds_dwordx4 v206, s[98:99]
	s_waitcnt vmcnt(8)
	s_waitcnt lgkmcnt(0)
	s_barrier
	v_mfma_f32_16x16x32_bf16 v[60:63], v[120:123], v[164:167], v[60:63]
	v_mfma_f32_16x16x32_bf16 v[56:59], v[132:135], v[164:167], v[56:59]
	v_mfma_f32_16x16x32_bf16 v[44:47], v[120:123], v[172:175], v[44:47]
	v_mfma_f32_16x16x32_bf16 v[40:43], v[132:135], v[172:175], v[40:43]
	v_mfma_f32_16x16x32_bf16 v[28:31], v[120:123], v[180:183], v[28:31]
	v_mfma_f32_16x16x32_bf16 v[24:27], v[132:135], v[180:183], v[24:27]
	v_mfma_f32_16x16x32_bf16 v[12:15], v[120:123], v[188:191], v[12:15]
	v_mfma_f32_16x16x32_bf16 v[8:11], v[132:135], v[188:191], v[8:11]
	v_mfma_f32_16x16x32_bf16 v[60:63], v[128:131], v[168:171], v[60:63]
	v_mfma_f32_16x16x32_bf16 v[56:59], v[136:139], v[168:171], v[56:59]
	v_mfma_f32_16x16x32_bf16 v[44:47], v[128:131], v[176:179], v[44:47]
	v_mfma_f32_16x16x32_bf16 v[40:43], v[136:139], v[176:179], v[40:43]
	v_mfma_f32_16x16x32_bf16 v[28:31], v[128:131], v[184:187], v[28:31]
	v_mfma_f32_16x16x32_bf16 v[24:27], v[136:139], v[184:187], v[24:27]
	v_mfma_f32_16x16x32_bf16 v[12:15], v[128:131], v[214:217], v[12:15]
	v_mfma_f32_16x16x32_bf16 v[8:11], v[136:139], v[214:217], v[8:11]
	v_mfma_f32_16x16x32_bf16 v[52:55], v[140:143], v[164:167], v[52:55]
	v_mfma_f32_16x16x32_bf16 v[48:51], v[156:159], v[164:167], v[48:51]
	v_mfma_f32_16x16x32_bf16 v[36:39], v[140:143], v[172:175], v[36:39]
	v_mfma_f32_16x16x32_bf16 v[32:35], v[156:159], v[172:175], v[32:35]
	v_mfma_f32_16x16x32_bf16 v[20:23], v[140:143], v[180:183], v[20:23]
	v_mfma_f32_16x16x32_bf16 v[16:19], v[156:159], v[180:183], v[16:19]
	v_mfma_f32_16x16x32_bf16 v[4:7], v[140:143], v[188:191], v[4:7]
	v_mfma_f32_16x16x32_bf16 v[0:3], v[156:159], v[188:191], v[0:3]
	v_mfma_f32_16x16x32_bf16 v[52:55], v[144:147], v[168:171], v[52:55]
	v_mfma_f32_16x16x32_bf16 v[48:51], v[160:163], v[168:171], v[48:51]
	v_mfma_f32_16x16x32_bf16 v[36:39], v[144:147], v[176:179], v[36:39]
	v_mfma_f32_16x16x32_bf16 v[32:35], v[160:163], v[176:179], v[32:35]
	v_mfma_f32_16x16x32_bf16 v[20:23], v[144:147], v[184:187], v[20:23]
	v_mfma_f32_16x16x32_bf16 v[16:19], v[160:163], v[184:187], v[16:19]
	v_mfma_f32_16x16x32_bf16 v[4:7], v[144:147], v[214:217], v[4:7]
	v_mfma_f32_16x16x32_bf16 v[0:3], v[160:163], v[214:217], v[0:3]
	s_barrier
	s_add_i32 s58, s58, 2
	s_add_u32 s62, s62, 0x100
	s_addc_u32 s63, s63, 0
	s_cmp_gt_u32 s58, 13
	s_cbranch_scc0 .LBB0_514
	s_and_b64 vcc, exec, s[14:15]
	s_cbranch_vccz .LBB0_517
	s_barrier

; #define PG8_STAGE(bufoff, gbase, voff) do { _Pragma("unroll") for (int _i = 0; _i < 2; ++_i) \
;         __builtin_amdgcn_global_load_lds((const unsigned*)((const char*)(gbase) + (voff)[_i]), (PG8_LAS unsigned*)(lds + (bufoff) + ldsw + _i * 8192), 16, 0, 0); } while (0)
; #define PG8_LDA(dst, b, h) do { _Pragma("unroll") for (int m = 0; m < 4; ++m) _Pragma("unroll") for (int k = 0; k < 2; ++k) dst[m][k] = *(const PG8_LAS bf16x8*)(lds + PG8_SA(b, h) + aoff + m * 2048 + k * 1024); } while (0)
; #define PG8_MMA(ai, bj, At, Bt) do { __builtin_amdgcn_s_setprio(1); _Pragma("unroll") for (int m = 0; m < 4; ++m) _Pragma("unroll") for (int n = 0; n < 2; ++n) _Pragma("unroll") for (int k = 0; k < 2; ++k) \
;         acc[ai][bj][m][n] = __builtin_amdgcn_mfma_f32_16x16x32_bf16(Bt[n][k], At[m][k], acc[ai][bj][m][n], 0, 0, 0); __builtin_amdgcn_s_setprio(0); } while (0)
; #define PG8_WAIT_L(n) asm volatile("s_waitcnt lgkmcnt(" #n ")" ::: "memory")
; #define PG8_WAIT_V8_UNLESS(flag) asm volatile("s_cmp_lg_i32 %0, 0\n\ts_cbranch_scc1 .Lpg8rx%=\n\ts_waitcnt vmcnt(8)\n.Lpg8rx%=:" :: "s"(__builtin_amdgcn_readfirstlane(flag)) : "scc", "memory")
; #define PG8_BAR __builtin_amdgcn_s_barrier()
; #define PG8_SCHED __builtin_amdgcn_sched_barrier(0)
; template <class Epi, class Sched, bool ALIGN_EPI = false, bool SP2 = false>
; __device__ __forceinline__ void gemm_phase(PG8_LAS unsigned char* lds, const Gemm g, const Sched& S, const Epi& E) {
;     ...
;             PG8_WAIT_V8_UNLESS(rx); PG8_WAIT_L(0); PG8_BAR; PG8_MMA(0, 0, At, B0); PG8_MMA(0, 1, At, B1); PG8_BAR; PG8_SCHED;
;             PG8_STAGE(PG8_SB(0, 0), b2, voffB); PG8_STAGE(PG8_SB(0, 1), b2 + hstep, voffB); PG8_STAGE(PG8_SA(0, 0), a2, voffA); PG8_SCHED; PG8_LDA(At, 0, 1);
;             PG8_WAIT_V8_UNLESS(rx); PG8_WAIT_L(0); PG8_BAR; PG8_MMA(1, 0, At, B0); PG8_MMA(1, 1, At, B1); PG8_BAR; PG8_SCHED;
.Lpg8rx4:
	s_waitcnt lgkmcnt(0)
	s_barrier
	v_mfma_f32_16x16x32_bf16 v[124:127], v[132:135], v[176:179], v[124:127]
	v_mfma_f32_16x16x32_bf16 v[120:123], v[140:143], v[176:179], v[120:123]
	v_mfma_f32_16x16x32_bf16 v[108:111], v[132:135], v[204:207], v[108:111]
	v_mfma_f32_16x16x32_bf16 v[104:107], v[140:143], v[204:207], v[104:107]
	v_mfma_f32_16x16x32_bf16 v[92:95], v[132:135], v[212:215], v[92:95]
	v_mfma_f32_16x16x32_bf16 v[88:91], v[140:143], v[212:215], v[88:91]
	v_mfma_f32_16x16x32_bf16 v[76:79], v[132:135], v[220:223], v[76:79]
	v_mfma_f32_16x16x32_bf16 v[72:75], v[140:143], v[220:223], v[72:75]
	v_mfma_f32_16x16x32_bf16 v[124:127], v[136:139], v[186:189], v[124:127]
	v_mfma_f32_16x16x32_bf16 v[120:123], v[144:147], v[186:189], v[120:123]
	v_mfma_f32_16x16x32_bf16 v[108:111], v[136:139], v[208:211], v[108:111]
	v_mfma_f32_16x16x32_bf16 v[104:107], v[144:147], v[208:211], v[104:107]
	v_mfma_f32_16x16x32_bf16 v[92:95], v[136:139], v[216:219], v[92:95]
	v_mfma_f32_16x16x32_bf16 v[88:91], v[144:147], v[216:219], v[88:91]
	v_mfma_f32_16x16x32_bf16 v[76:79], v[136:139], v[224:227], v[76:79]
	v_mfma_f32_16x16x32_bf16 v[72:75], v[144:147], v[224:227], v[72:75]
	v_mfma_f32_16x16x32_bf16 v[116:119], v[148:151], v[176:179], v[116:119]
	v_mfma_f32_16x16x32_bf16 v[112:115], v[168:171], v[176:179], v[112:115]
	v_mfma_f32_16x16x32_bf16 v[100:103], v[148:151], v[204:207], v[100:103]
	v_mfma_f32_16x16x32_bf16 v[96:99], v[168:171], v[204:207], v[96:99]
	v_mfma_f32_16x16x32_bf16 v[84:87], v[148:151], v[212:215], v[84:87]
	v_mfma_f32_16x16x32_bf16 v[80:83], v[168:171], v[212:215], v[80:83]
	v_mfma_f32_16x16x32_bf16 v[68:71], v[148:151], v[220:223], v[68:71]
	v_mfma_f32_16x16x32_bf16 v[64:67], v[168:171], v[220:223], v[64:67]
	v_mfma_f32_16x16x32_bf16 v[116:119], v[164:167], v[186:189], v[116:119]
	v_mfma_f32_16x16x32_bf16 v[112:115], v[172:175], v[186:189], v[112:115]
	v_mfma_f32_16x16x32_bf16 v[100:103], v[164:167], v[208:211], v[100:103]
	v_mfma_f32_16x16x32_bf16 v[96:99], v[172:175], v[208:211], v[96:99]
	v_mfma_f32_16x16x32_bf16 v[84:87], v[164:167], v[216:219], v[84:87]
	v_mfma_f32_16x16x32_bf16 v[80:83], v[172:175], v[216:219], v[80:83]
	v_mfma_f32_16x16x32_bf16 v[68:71], v[164:167], v[224:227], v[68:71]
	v_mfma_f32_16x16x32_bf16 v[64:67], v[172:175], v[224:227], v[64:67]
	s_barrier
	ds_read_b128 v[176:179], v185 offset:16384
	ds_read_b128 v[186:189], v185 offset:17408
	ds_read_b128 v[204:207], v185 offset:18432
	ds_read_b128 v[208:211], v185 offset:19456
	ds_read_b128 v[212:215], v185 offset:20480
	ds_read_b128 v[216:219], v185 offset:21504
	ds_read_b128 v[220:223], v185 offset:22528
	ds_read_b128 v[224:227], v185 offset:23552
	s_add_u32 s60, s28, 0x40000
	s_addc_u32 s61, s29, 0
	s_add_i32 m0, s59, s38
	s_nop 0
	global_load_lds_dwordx4 v154, s[28:29]
	s_add_i32 m0, m0, 0x2000
	s_nop 0
	global_load_lds_dwordx4 v158, s[28:29]
	s_add_i32 m0, s62, s38
	s_nop 0
	global_load_lds_dwordx4 v154, s[60:61]
	s_add_i32 m0, m0, 0x2000
	s_nop 0
	global_load_lds_dwordx4 v158, s[60:61]
	s_mov_b32 m0, s21
	s_nop 0
	global_load_lds_dwordx4 v152, s[30:31]
	s_mov_b32 m0, s23
	s_nop 0
	global_load_lds_dwordx4 v156, s[30:31]
	s_cmp_lg_i32 s63, 0
	s_cbranch_scc1 .Lpg8rx5
	s_waitcnt vmcnt(8)
.Lpg8rx5:
	s_waitcnt lgkmcnt(0)
	s_barrier
	v_mfma_f32_16x16x32_bf16 v[60:63], v[132:135], v[176:179], v[60:63]
	v_mfma_f32_16x16x32_bf16 v[56:59], v[140:143], v[176:179], v[56:59]
	v_mfma_f32_16x16x32_bf16 v[44:47], v[132:135], v[204:207], v[44:47]
	v_mfma_f32_16x16x32_bf16 v[40:43], v[140:143], v[204:207], v[40:43]
	v_mfma_f32_16x16x32_bf16 v[28:31], v[132:135], v[212:215], v[28:31]
	v_mfma_f32_16x16x32_bf16 v[24:27], v[140:143], v[212:215], v[24:27]
	v_mfma_f32_16x16x32_bf16 v[12:15], v[132:135], v[220:223], v[12:15]
	v_mfma_f32_16x16x32_bf16 v[8:11], v[140:143], v[220:223], v[8:11]
	v_mfma_f32_16x16x32_bf16 v[60:63], v[136:139], v[186:189], v[60:63]
	v_mfma_f32_16x16x32_bf16 v[56:59], v[144:147], v[186:189], v[56:59]
	v_mfma_f32_16x16x32_bf16 v[44:47], v[136:139], v[208:211], v[44:47]
	v_mfma_f32_16x16x32_bf16 v[40:43], v[144:147], v[208:211], v[40:43]
	v_mfma_f32_16x16x32_bf16 v[28:31], v[136:139], v[216:219], v[28:31]
	v_mfma_f32_16x16x32_bf16 v[24:27], v[144:147], v[216:219], v[24:27]
	v_mfma_f32_16x16x32_bf16 v[12:15], v[136:139], v[224:227], v[12:15]
	v_mfma_f32_16x16x32_bf16 v[8:11], v[144:147], v[224:227], v[8:11]
	v_mfma_f32_16x16x32_bf16 v[52:55], v[148:151], v[176:179], v[52:55]
	v_mfma_f32_16x16x32_bf16 v[48:51], v[168:171], v[176:179], v[48:51]
	v_mfma_f32_16x16x32_bf16 v[36:39], v[148:151], v[204:207], v[36:39]
	v_mfma_f32_16x16x32_bf16 v[32:35], v[168:171], v[204:207], v[32:35]
	v_mfma_f32_16x16x32_bf16 v[20:23], v[148:151], v[212:215], v[20:23]
	v_mfma_f32_16x16x32_bf16 v[16:19], v[168:171], v[212:215], v[16:19]
	v_mfma_f32_16x16x32_bf16 v[4:7], v[148:151], v[220:223], v[4:7]
	v_mfma_f32_16x16x32_bf16 v[0:3], v[168:171], v[220:223], v[0:3]
	v_mfma_f32_16x16x32_bf16 v[52:55], v[164:167], v[186:189], v[52:55]
	v_mfma_f32_16x16x32_bf16 v[48:51], v[172:175], v[186:189], v[48:51]
	v_mfma_f32_16x16x32_bf16 v[36:39], v[164:167], v[208:211], v[36:39]
	v_mfma_f32_16x16x32_bf16 v[32:35], v[172:175], v[208:211], v[32:35]
	v_mfma_f32_16x16x32_bf16 v[20:23], v[164:167], v[216:219], v[20:23]
	v_mfma_f32_16x16x32_bf16 v[16:19], v[172:175], v[216:219], v[16:19]
	v_mfma_f32_16x16x32_bf16 v[4:7], v[164:167], v[224:227], v[4:7]
	v_mfma_f32_16x16x32_bf16 v[0:3], v[172:175], v[224:227], v[0:3]
	s_barrier
; #define PG8_STAGE(bufoff, gbase, voff) do { _Pragma("unroll") for (int _i = 0; _i < 2; ++_i) \
;         __builtin_amdgcn_global_load_lds((const unsigned*)((const char*)(gbase) + (voff)[_i]), (PG8_LAS unsigned*)(lds + (bufoff) + ldsw + _i * 8192), 16, 0, 0); } while (0)
; #define PG8_LDA(dst, b, h) do { _Pragma("unroll") for (int m = 0; m < 4; ++m) _Pragma("unroll") for (int k = 0; k < 2; ++k) dst[m][k] = *(const PG8_LAS bf16x8*)(lds + PG8_SA(b, h) + aoff + m * 2048 + k * 1024); } while (0)
; #define PG8_LDB(dst, b, h) do { _Pragma("unroll") for (int n = 0; n < 2; ++n) _Pragma("unroll") for (int k = 0; k < 2; ++k) dst[n][k] = *(const PG8_LAS bf16x8*)(lds + PG8_SB(b, h) + boff + n * 2048 + k * 1024); } while (0)
; #define PG8_MMA(ai, bj, At, Bt) do { __builtin_amdgcn_s_setprio(1); _Pragma("unroll") for (int m = 0; m < 4; ++m) _Pragma("unroll") for (int n = 0; n < 2; ++n) _Pragma("unroll") for (int k = 0; k < 2; ++k) \
;         acc[ai][bj][m][n] = __builtin_amdgcn_mfma_f32_16x16x32_bf16(Bt[n][k], At[m][k], acc[ai][bj][m][n], 0, 0, 0); __builtin_amdgcn_s_setprio(0); } while (0)
; #define PG8_WAIT_V(n) asm volatile("s_waitcnt vmcnt(" #n ")" ::: "memory")
; #define PG8_WAIT_L(n) asm volatile("s_waitcnt lgkmcnt(" #n ")" ::: "memory")
; #define PG8_BAR __builtin_amdgcn_s_barrier()
; #define PG8_SCHED __builtin_amdgcn_sched_barrier(0)
; template <class Epi, class Sched, bool ALIGN_EPI = false, bool SP2 = false>
; __device__ __forceinline__ void gemm_phase(PG8_LAS unsigned char* lds, const Gemm g, const Sched& S, const Epi& E) {
;     ...
;         for (int t = 0; t < nt; t += 2) {
;     ...
;             PG8_STAGE(PG8_SA(0, 1), a2 + hstep, voffA); PG8_SCHED; PG8_LDB(B0, 1, 0); PG8_LDB(B1, 1, 1); PG8_SCHED; PG8_LDA(At, 1, 0);
;             PG8_WAIT_V(8); PG8_WAIT_L(0); PG8_BAR; PG8_MMA(0, 0, At, B0); PG8_MMA(0, 1, At, B1); PG8_BAR; PG8_SCHED;
;             PG8_STAGE(PG8_SB(1, 0), b3, voffB); PG8_STAGE(PG8_SB(1, 1), b3 + hstep, voffB); PG8_STAGE(PG8_SA(1, 0), a3, voffA); PG8_SCHED; PG8_LDA(At, 1, 1);
;             PG8_WAIT_V(8); PG8_WAIT_L(0); PG8_BAR; PG8_MMA(1, 0, At, B0); PG8_MMA(1, 1, At, B1); PG8_BAR; PG8_SCHED;
	s_mov_b64 s[98:99], s[30:31]
	s_add_u32 s100, s30, 0x40000
	s_addc_u32 s101, s31, 0
	s_add_i32 s30, 0, 0x18000
	s_add_i32 s31, 0, 0x1c000
	v_add_u32_e32 v144, s30, v183
	v_add_u32_e32 v172, s31, v183
	ds_read_b128 v[132:135], v144
	ds_read_b128 v[136:139], v144 offset:1024
	ds_read_b128 v[140:143], v144 offset:2048
	ds_read_b128 v[144:147], v144 offset:3072
	ds_read_b128 v[148:151], v172
	ds_read_b128 v[164:167], v172 offset:1024
	ds_read_b128 v[168:171], v172 offset:2048
	ds_read_b128 v[172:175], v172 offset:3072
	ds_read_b128 v[176:179], v185 offset:32768
	ds_read_b128 v[186:189], v185 offset:33792
	ds_read_b128 v[204:207], v185 offset:34816
	ds_read_b128 v[208:211], v185 offset:35840
	ds_read_b128 v[212:215], v185 offset:36864
	ds_read_b128 v[216:219], v185 offset:37888
	ds_read_b128 v[220:223], v185 offset:38912
	ds_read_b128 v[224:227], v185 offset:39936
	s_mov_b32 m0, s46
	s_nop 0
	global_load_lds_dwordx4 v152, s[100:101]
	s_mov_b32 m0, s48
	s_nop 0
	global_load_lds_dwordx4 v156, s[100:101]
	s_waitcnt vmcnt(8)
	s_waitcnt lgkmcnt(0)
	s_barrier
	v_mfma_f32_16x16x32_bf16 v[124:127], v[132:135], v[176:179], v[124:127]
	v_mfma_f32_16x16x32_bf16 v[120:123], v[140:143], v[176:179], v[120:123]
	v_mfma_f32_16x16x32_bf16 v[108:111], v[132:135], v[204:207], v[108:111]
	v_mfma_f32_16x16x32_bf16 v[104:107], v[140:143], v[204:207], v[104:107]
	v_mfma_f32_16x16x32_bf16 v[92:95], v[132:135], v[212:215], v[92:95]
	v_mfma_f32_16x16x32_bf16 v[88:91], v[140:143], v[212:215], v[88:91]
	v_mfma_f32_16x16x32_bf16 v[76:79], v[132:135], v[220:223], v[76:79]
	v_mfma_f32_16x16x32_bf16 v[72:75], v[140:143], v[220:223], v[72:75]
	v_mfma_f32_16x16x32_bf16 v[124:127], v[136:139], v[186:189], v[124:127]
	v_mfma_f32_16x16x32_bf16 v[120:123], v[144:147], v[186:189], v[120:123]
	v_mfma_f32_16x16x32_bf16 v[108:111], v[136:139], v[208:211], v[108:111]
	v_mfma_f32_16x16x32_bf16 v[104:107], v[144:147], v[208:211], v[104:107]
	v_mfma_f32_16x16x32_bf16 v[92:95], v[136:139], v[216:219], v[92:95]
	v_mfma_f32_16x16x32_bf16 v[88:91], v[144:147], v[216:219], v[88:91]
	v_mfma_f32_16x16x32_bf16 v[76:79], v[136:139], v[224:227], v[76:79]
	v_mfma_f32_16x16x32_bf16 v[72:75], v[144:147], v[224:227], v[72:75]
	v_mfma_f32_16x16x32_bf16 v[116:119], v[148:151], v[176:179], v[116:119]
	v_mfma_f32_16x16x32_bf16 v[112:115], v[168:171], v[176:179], v[112:115]
	v_mfma_f32_16x16x32_bf16 v[100:103], v[148:151], v[204:207], v[100:103]
	v_mfma_f32_16x16x32_bf16 v[96:99], v[168:171], v[204:207], v[96:99]
	v_mfma_f32_16x16x32_bf16 v[84:87], v[148:151], v[212:215], v[84:87]
	v_mfma_f32_16x16x32_bf16 v[80:83], v[168:171], v[212:215], v[80:83]
	v_mfma_f32_16x16x32_bf16 v[68:71], v[148:151], v[220:223], v[68:71]
	v_mfma_f32_16x16x32_bf16 v[64:67], v[168:171], v[220:223], v[64:67]
	v_mfma_f32_16x16x32_bf16 v[116:119], v[164:167], v[186:189], v[116:119]
	v_mfma_f32_16x16x32_bf16 v[112:115], v[172:175], v[186:189], v[112:115]
	v_mfma_f32_16x16x32_bf16 v[100:103], v[164:167], v[208:211], v[100:103]
	v_mfma_f32_16x16x32_bf16 v[96:99], v[172:175], v[208:211], v[96:99]
	v_mfma_f32_16x16x32_bf16 v[84:87], v[164:167], v[216:219], v[84:87]
	v_mfma_f32_16x16x32_bf16 v[80:83], v[172:175], v[216:219], v[80:83]
	v_mfma_f32_16x16x32_bf16 v[68:71], v[164:167], v[224:227], v[68:71]
	v_mfma_f32_16x16x32_bf16 v[64:67], v[172:175], v[224:227], v[64:67]
	s_barrier
	ds_read_b128 v[176:179], v185 offset:49152
	ds_read_b128 v[186:189], v185 offset:50176
	ds_read_b128 v[204:207], v185 offset:51200
	ds_read_b128 v[208:211], v185 offset:52224
	ds_read_b128 v[212:215], v185 offset:53248
	ds_read_b128 v[216:219], v185 offset:54272
	ds_read_b128 v[220:223], v185 offset:55296
	ds_read_b128 v[224:227], v185 offset:56320
	s_add_u32 s100, s28, 0x80
	s_addc_u32 s101, s29, 0
	s_add_u32 s28, s28, 0x40080
	s_addc_u32 s29, s29, 0
	s_add_u32 s98, s98, 0x80
	s_addc_u32 s99, s99, 0
	s_add_i32 m0, s30, s38
	s_nop 0
	global_load_lds_dwordx4 v154, s[100:101]
	s_add_i32 m0, m0, 0x2000
	s_nop 0
	global_load_lds_dwordx4 v158, s[100:101]
	s_add_i32 m0, s31, s38
	s_nop 0
	global_load_lds_dwordx4 v154, s[28:29]
	s_add_i32 m0, m0, 0x2000
	s_nop 0
	global_load_lds_dwordx4 v158, s[28:29]
	s_mov_b32 m0, s50
	s_nop 0
	global_load_lds_dwordx4 v152, s[98:99]
	s_mov_b32 m0, s51
	s_nop 0
	global_load_lds_dwordx4 v156, s[98:99]
	s_waitcnt vmcnt(8)
	s_waitcnt lgkmcnt(0)
	s_barrier
	v_mfma_f32_16x16x32_bf16 v[60:63], v[132:135], v[176:179], v[60:63]
	v_mfma_f32_16x16x32_bf16 v[56:59], v[140:143], v[176:179], v[56:59]
	v_mfma_f32_16x16x32_bf16 v[44:47], v[132:135], v[204:207], v[44:47]
	v_mfma_f32_16x16x32_bf16 v[40:43], v[140:143], v[204:207], v[40:43]
	v_mfma_f32_16x16x32_bf16 v[28:31], v[132:135], v[212:215], v[28:31]
	v_mfma_f32_16x16x32_bf16 v[24:27], v[140:143], v[212:215], v[24:27]
	v_mfma_f32_16x16x32_bf16 v[12:15], v[132:135], v[220:223], v[12:15]
	v_mfma_f32_16x16x32_bf16 v[8:11], v[140:143], v[220:223], v[8:11]
	v_mfma_f32_16x16x32_bf16 v[60:63], v[136:139], v[186:189], v[60:63]
	v_mfma_f32_16x16x32_bf16 v[56:59], v[144:147], v[186:189], v[56:59]
	v_mfma_f32_16x16x32_bf16 v[44:47], v[136:139], v[208:211], v[44:47]
	v_mfma_f32_16x16x32_bf16 v[40:43], v[144:147], v[208:211], v[40:43]
	v_mfma_f32_16x16x32_bf16 v[28:31], v[136:139], v[216:219], v[28:31]
	v_mfma_f32_16x16x32_bf16 v[24:27], v[144:147], v[216:219], v[24:27]
	v_mfma_f32_16x16x32_bf16 v[12:15], v[136:139], v[224:227], v[12:15]
	v_mfma_f32_16x16x32_bf16 v[8:11], v[144:147], v[224:227], v[8:11]
	v_mfma_f32_16x16x32_bf16 v[52:55], v[148:151], v[176:179], v[52:55]
	v_mfma_f32_16x16x32_bf16 v[48:51], v[168:171], v[176:179], v[48:51]
	v_mfma_f32_16x16x32_bf16 v[36:39], v[148:151], v[204:207], v[36:39]
	v_mfma_f32_16x16x32_bf16 v[32:35], v[168:171], v[204:207], v[32:35]
	v_mfma_f32_16x16x32_bf16 v[20:23], v[148:151], v[212:215], v[20:23]
	v_mfma_f32_16x16x32_bf16 v[16:19], v[168:171], v[212:215], v[16:19]
	v_mfma_f32_16x16x32_bf16 v[4:7], v[148:151], v[220:223], v[4:7]
	v_mfma_f32_16x16x32_bf16 v[0:3], v[168:171], v[220:223], v[0:3]
	v_mfma_f32_16x16x32_bf16 v[52:55], v[164:167], v[186:189], v[52:55]
	v_mfma_f32_16x16x32_bf16 v[48:51], v[172:175], v[186:189], v[48:51]
	v_mfma_f32_16x16x32_bf16 v[36:39], v[164:167], v[208:211], v[36:39]
	v_mfma_f32_16x16x32_bf16 v[32:35], v[172:175], v[208:211], v[32:35]
	v_mfma_f32_16x16x32_bf16 v[20:23], v[164:167], v[216:219], v[20:23]
	v_mfma_f32_16x16x32_bf16 v[16:19], v[172:175], v[216:219], v[16:19]
	v_mfma_f32_16x16x32_bf16 v[4:7], v[164:167], v[224:227], v[4:7]
	v_mfma_f32_16x16x32_bf16 v[0:3], v[172:175], v[224:227], v[0:3]
	s_barrier
	s_add_i32 s58, s58, 2
	s_add_u32 s40, s40, 0x100
	s_addc_u32 s41, s41, 0
	s_cmp_gt_u32 s58, 13
	s_cbranch_scc0 .LBB0_611
	s_and_b64 vcc, exec, s[8:9]
	s_cbranch_vccz .LBB0_614
	s_barrier

; #define PG8_STAGE(bufoff, gbase, voff) do { _Pragma("unroll") for (int _i = 0; _i < 2; ++_i) \
;         __builtin_amdgcn_global_load_lds((const unsigned*)((const char*)(gbase) + (voff)[_i]), (PG8_LAS unsigned*)(lds + (bufoff) + ldsw + _i * 8192), 16, 0, 0); } while (0)
; #define PG8_LDA(dst, b, h) do { _Pragma("unroll") for (int m = 0; m < 4; ++m) _Pragma("unroll") for (int k = 0; k < 2; ++k) dst[m][k] = *(const PG8_LAS bf16x8*)(lds + PG8_SA(b, h) + aoff + m * 2048 + k * 1024); } while (0)
; #define PG8_MMA(ai, bj, At, Bt) do { __builtin_amdgcn_s_setprio(1); _Pragma("unroll") for (int m = 0; m < 4; ++m) _Pragma("unroll") for (int n = 0; n < 2; ++n) _Pragma("unroll") for (int k = 0; k < 2; ++k) \
;         acc[ai][bj][m][n] = __builtin_amdgcn_mfma_f32_16x16x32_bf16(Bt[n][k], At[m][k], acc[ai][bj][m][n], 0, 0, 0); __builtin_amdgcn_s_setprio(0); } while (0)
; #define PG8_WAIT_L(n) asm volatile("s_waitcnt lgkmcnt(" #n ")" ::: "memory")
; #define PG8_WAIT_V8_UNLESS(flag) asm volatile("s_cmp_lg_i32 %0, 0\n\ts_cbranch_scc1 .Lpg8rx%=\n\ts_waitcnt vmcnt(8)\n.Lpg8rx%=:" :: "s"(__builtin_amdgcn_readfirstlane(flag)) : "scc", "memory")
; #define PG8_BAR __builtin_amdgcn_s_barrier()
; #define PG8_SCHED __builtin_amdgcn_sched_barrier(0)
; template <class Epi, class Sched, bool ALIGN_EPI = false, bool SP2 = false>
; __device__ __forceinline__ void gemm_phase(PG8_LAS unsigned char* lds, const Gemm g, const Sched& S, const Epi& E) {
;     ...
;             PG8_WAIT_V8_UNLESS(rx); PG8_WAIT_L(0); PG8_BAR; PG8_MMA(0, 0, At, B0); PG8_MMA(0, 1, At, B1); PG8_BAR; PG8_SCHED;
;             PG8_STAGE(PG8_SB(0, 0), b2, voffB); PG8_STAGE(PG8_SB(0, 1), b2 + hstep, voffB); PG8_STAGE(PG8_SA(0, 0), a2, voffA); PG8_SCHED; PG8_LDA(At, 0, 1);
;             PG8_WAIT_V8_UNLESS(rx); PG8_WAIT_L(0); PG8_BAR; PG8_MMA(1, 0, At, B0); PG8_MMA(1, 1, At, B1); PG8_BAR; PG8_SCHED;
.Lpg8rx6:
	s_waitcnt lgkmcnt(0)
	s_barrier
	v_mfma_f32_16x16x32_bf16 v[152:155], v[120:123], v[164:167], v[152:155]
	v_mfma_f32_16x16x32_bf16 v[148:151], v[132:135], v[164:167], v[148:151]
	v_mfma_f32_16x16x32_bf16 v[108:111], v[120:123], v[172:175], v[108:111]
	v_mfma_f32_16x16x32_bf16 v[104:107], v[132:135], v[172:175], v[104:107]
	v_mfma_f32_16x16x32_bf16 v[92:95], v[120:123], v[180:183], v[92:95]
	v_mfma_f32_16x16x32_bf16 v[88:91], v[132:135], v[180:183], v[88:91]
	v_mfma_f32_16x16x32_bf16 v[76:79], v[120:123], v[188:191], v[76:79]
	v_mfma_f32_16x16x32_bf16 v[72:75], v[132:135], v[188:191], v[72:75]
	v_mfma_f32_16x16x32_bf16 v[152:155], v[128:131], v[168:171], v[152:155]
	v_mfma_f32_16x16x32_bf16 v[148:151], v[136:139], v[168:171], v[148:151]
	v_mfma_f32_16x16x32_bf16 v[108:111], v[128:131], v[176:179], v[108:111]
	v_mfma_f32_16x16x32_bf16 v[104:107], v[136:139], v[176:179], v[104:107]
	v_mfma_f32_16x16x32_bf16 v[92:95], v[128:131], v[184:187], v[92:95]
	v_mfma_f32_16x16x32_bf16 v[88:91], v[136:139], v[184:187], v[88:91]
	v_mfma_f32_16x16x32_bf16 v[76:79], v[128:131], v[214:217], v[76:79]
	v_mfma_f32_16x16x32_bf16 v[72:75], v[136:139], v[214:217], v[72:75]
	v_mfma_f32_16x16x32_bf16 v[124:127], v[140:143], v[164:167], v[124:127]
	v_mfma_f32_16x16x32_bf16 v[112:115], v[156:159], v[164:167], v[112:115]
	v_mfma_f32_16x16x32_bf16 v[100:103], v[140:143], v[172:175], v[100:103]
	v_mfma_f32_16x16x32_bf16 v[96:99], v[156:159], v[172:175], v[96:99]
	v_mfma_f32_16x16x32_bf16 v[84:87], v[140:143], v[180:183], v[84:87]
	v_mfma_f32_16x16x32_bf16 v[80:83], v[156:159], v[180:183], v[80:83]
	v_mfma_f32_16x16x32_bf16 v[68:71], v[140:143], v[188:191], v[68:71]
	v_mfma_f32_16x16x32_bf16 v[64:67], v[156:159], v[188:191], v[64:67]
	v_mfma_f32_16x16x32_bf16 v[124:127], v[144:147], v[168:171], v[124:127]
	v_mfma_f32_16x16x32_bf16 v[112:115], v[160:163], v[168:171], v[112:115]
	v_mfma_f32_16x16x32_bf16 v[100:103], v[144:147], v[176:179], v[100:103]
	v_mfma_f32_16x16x32_bf16 v[96:99], v[160:163], v[176:179], v[96:99]
	v_mfma_f32_16x16x32_bf16 v[84:87], v[144:147], v[184:187], v[84:87]
	v_mfma_f32_16x16x32_bf16 v[80:83], v[160:163], v[184:187], v[80:83]
	v_mfma_f32_16x16x32_bf16 v[68:71], v[144:147], v[214:217], v[68:71]
	v_mfma_f32_16x16x32_bf16 v[64:67], v[160:163], v[214:217], v[64:67]
	s_barrier
	ds_read_b128 v[164:167], v248 offset:16384
	ds_read_b128 v[168:171], v248 offset:17408
	ds_read_b128 v[172:175], v248 offset:18432
	ds_read_b128 v[176:179], v248 offset:19456
	ds_read_b128 v[180:183], v248 offset:20480
	ds_read_b128 v[184:187], v248 offset:21504
	ds_read_b128 v[188:191], v248 offset:22528
	ds_read_b128 v[214:217], v248 offset:23552
	s_add_u32 s58, s28, 0x100000
	s_addc_u32 s59, s29, 0
	s_add_i32 m0, s57, s39
	s_nop 0
	global_load_lds_dwordx4 v194, s[28:29]
	s_add_i32 m0, m0, 0x2000
	s_nop 0
	global_load_lds_dwordx4 v208, s[28:29]
	s_add_i32 m0, s60, s39
	s_nop 0
	global_load_lds_dwordx4 v194, s[58:59]
	s_add_i32 m0, m0, 0x2000
	s_nop 0
	global_load_lds_dwordx4 v208, s[58:59]
	s_mov_b32 m0, s25
	s_nop 0
	global_load_lds_dwordx4 v204, s[30:31]
	s_mov_b32 m0, s42
	s_nop 0
	global_load_lds_dwordx4 v206, s[30:31]
	s_cmp_lg_i32 s61, 0
	s_cbranch_scc1 .Lpg8rx7
	s_waitcnt vmcnt(8)
.Lpg8rx7:
	s_waitcnt lgkmcnt(0)
	s_barrier
	v_mfma_f32_16x16x32_bf16 v[60:63], v[120:123], v[164:167], v[60:63]
	v_mfma_f32_16x16x32_bf16 v[56:59], v[132:135], v[164:167], v[56:59]
	v_mfma_f32_16x16x32_bf16 v[44:47], v[120:123], v[172:175], v[44:47]
	v_mfma_f32_16x16x32_bf16 v[40:43], v[132:135], v[172:175], v[40:43]
	v_mfma_f32_16x16x32_bf16 v[28:31], v[120:123], v[180:183], v[28:31]
	v_mfma_f32_16x16x32_bf16 v[24:27], v[132:135], v[180:183], v[24:27]
	v_mfma_f32_16x16x32_bf16 v[12:15], v[120:123], v[188:191], v[12:15]
	v_mfma_f32_16x16x32_bf16 v[8:11], v[132:135], v[188:191], v[8:11]
	v_mfma_f32_16x16x32_bf16 v[60:63], v[128:131], v[168:171], v[60:63]
	v_mfma_f32_16x16x32_bf16 v[56:59], v[136:139], v[168:171], v[56:59]
	v_mfma_f32_16x16x32_bf16 v[44:47], v[128:131], v[176:179], v[44:47]
	v_mfma_f32_16x16x32_bf16 v[40:43], v[136:139], v[176:179], v[40:43]
	v_mfma_f32_16x16x32_bf16 v[28:31], v[128:131], v[184:187], v[28:31]
	v_mfma_f32_16x16x32_bf16 v[24:27], v[136:139], v[184:187], v[24:27]
	v_mfma_f32_16x16x32_bf16 v[12:15], v[128:131], v[214:217], v[12:15]
	v_mfma_f32_16x16x32_bf16 v[8:11], v[136:139], v[214:217], v[8:11]
	v_mfma_f32_16x16x32_bf16 v[52:55], v[140:143], v[164:167], v[52:55]
	v_mfma_f32_16x16x32_bf16 v[48:51], v[156:159], v[164:167], v[48:51]
	v_mfma_f32_16x16x32_bf16 v[36:39], v[140:143], v[172:175], v[36:39]
	v_mfma_f32_16x16x32_bf16 v[32:35], v[156:159], v[172:175], v[32:35]
	v_mfma_f32_16x16x32_bf16 v[20:23], v[140:143], v[180:183], v[20:23]
	v_mfma_f32_16x16x32_bf16 v[16:19], v[156:159], v[180:183], v[16:19]
	v_mfma_f32_16x16x32_bf16 v[4:7], v[140:143], v[188:191], v[4:7]
	v_mfma_f32_16x16x32_bf16 v[0:3], v[156:159], v[188:191], v[0:3]
	v_mfma_f32_16x16x32_bf16 v[52:55], v[144:147], v[168:171], v[52:55]
	v_mfma_f32_16x16x32_bf16 v[48:51], v[160:163], v[168:171], v[48:51]
	v_mfma_f32_16x16x32_bf16 v[36:39], v[144:147], v[176:179], v[36:39]
	v_mfma_f32_16x16x32_bf16 v[32:35], v[160:163], v[176:179], v[32:35]
	v_mfma_f32_16x16x32_bf16 v[20:23], v[144:147], v[184:187], v[20:23]
	v_mfma_f32_16x16x32_bf16 v[16:19], v[160:163], v[184:187], v[16:19]
	v_mfma_f32_16x16x32_bf16 v[4:7], v[144:147], v[214:217], v[4:7]
	v_mfma_f32_16x16x32_bf16 v[0:3], v[160:163], v[214:217], v[0:3]
	s_barrier
; #define PG8_STAGE(bufoff, gbase, voff) do { _Pragma("unroll") for (int _i = 0; _i < 2; ++_i) \
;         __builtin_amdgcn_global_load_lds((const unsigned*)((const char*)(gbase) + (voff)[_i]), (PG8_LAS unsigned*)(lds + (bufoff) + ldsw + _i * 8192), 16, 0, 0); } while (0)
; #define PG8_LDA(dst, b, h) do { _Pragma("unroll") for (int m = 0; m < 4; ++m) _Pragma("unroll") for (int k = 0; k < 2; ++k) dst[m][k] = *(const PG8_LAS bf16x8*)(lds + PG8_SA(b, h) + aoff + m * 2048 + k * 1024); } while (0)
; #define PG8_LDB(dst, b, h) do { _Pragma("unroll") for (int n = 0; n < 2; ++n) _Pragma("unroll") for (int k = 0; k < 2; ++k) dst[n][k] = *(const PG8_LAS bf16x8*)(lds + PG8_SB(b, h) + boff + n * 2048 + k * 1024); } while (0)
; #define PG8_MMA(ai, bj, At, Bt) do { __builtin_amdgcn_s_setprio(1); _Pragma("unroll") for (int m = 0; m < 4; ++m) _Pragma("unroll") for (int n = 0; n < 2; ++n) _Pragma("unroll") for (int k = 0; k < 2; ++k) \
;         acc[ai][bj][m][n] = __builtin_amdgcn_mfma_f32_16x16x32_bf16(Bt[n][k], At[m][k], acc[ai][bj][m][n], 0, 0, 0); __builtin_amdgcn_s_setprio(0); } while (0)
; #define PG8_WAIT_V(n) asm volatile("s_waitcnt vmcnt(" #n ")" ::: "memory")
; #define PG8_WAIT_L(n) asm volatile("s_waitcnt lgkmcnt(" #n ")" ::: "memory")
; #define PG8_BAR __builtin_amdgcn_s_barrier()
; #define PG8_SCHED __builtin_amdgcn_sched_barrier(0)
; template <class Epi, class Sched, bool ALIGN_EPI = false, bool SP2 = false>
; __device__ __forceinline__ void gemm_phase(PG8_LAS unsigned char* lds, const Gemm g, const Sched& S, const Epi& E) {
;     ...
;         for (int t = 0; t < nt; t += 2) {
;     ...
;             PG8_STAGE(PG8_SA(0, 1), a2 + hstep, voffA); PG8_SCHED; PG8_LDB(B0, 1, 0); PG8_LDB(B1, 1, 1); PG8_SCHED; PG8_LDA(At, 1, 0);
;             PG8_WAIT_V(8); PG8_WAIT_L(0); PG8_BAR; PG8_MMA(0, 0, At, B0); PG8_MMA(0, 1, At, B1); PG8_BAR; PG8_SCHED;
;             PG8_STAGE(PG8_SB(1, 0), b3, voffB); PG8_STAGE(PG8_SB(1, 1), b3 + hstep, voffB); PG8_STAGE(PG8_SA(1, 0), a3, voffA); PG8_SCHED; PG8_LDA(At, 1, 1);
;             PG8_WAIT_V(8); PG8_WAIT_L(0); PG8_BAR; PG8_MMA(1, 0, At, B0); PG8_MMA(1, 1, At, B1); PG8_BAR; PG8_SCHED;
	s_mov_b64 s[98:99], s[30:31]
	s_add_u32 s100, s30, 0x100000
	s_addc_u32 s101, s31, 0
	s_add_i32 s30, 0, 0x18000
	s_add_i32 s31, 0, 0x1c000
	v_add_u32_e32 v136, s30, v247
	v_add_u32_e32 v160, s31, v247
	ds_read_b128 v[120:123], v136
	ds_read_b128 v[128:131], v136 offset:1024
	ds_read_b128 v[132:135], v136 offset:2048
	ds_read_b128 v[136:139], v136 offset:3072
	ds_read_b128 v[140:143], v160
	ds_read_b128 v[144:147], v160 offset:1024
	ds_read_b128 v[156:159], v160 offset:2048
	ds_read_b128 v[160:163], v160 offset:3072
	ds_read_b128 v[164:167], v248 offset:32768
	ds_read_b128 v[168:171], v248 offset:33792
	ds_read_b128 v[172:175], v248 offset:34816
	ds_read_b128 v[176:179], v248 offset:35840
	ds_read_b128 v[180:183], v248 offset:36864
	ds_read_b128 v[184:187], v248 offset:37888
	ds_read_b128 v[188:191], v248 offset:38912
	ds_read_b128 v[214:217], v248 offset:39936
	s_mov_b32 m0, s43
	s_nop 0
	global_load_lds_dwordx4 v204, s[100:101]
	s_mov_b32 m0, s44
	s_nop 0
	global_load_lds_dwordx4 v206, s[100:101]
	s_waitcnt vmcnt(8)
	s_waitcnt lgkmcnt(0)
	s_barrier
	v_mfma_f32_16x16x32_bf16 v[152:155], v[120:123], v[164:167], v[152:155]
	v_mfma_f32_16x16x32_bf16 v[148:151], v[132:135], v[164:167], v[148:151]
	v_mfma_f32_16x16x32_bf16 v[108:111], v[120:123], v[172:175], v[108:111]
	v_mfma_f32_16x16x32_bf16 v[104:107], v[132:135], v[172:175], v[104:107]
	v_mfma_f32_16x16x32_bf16 v[92:95], v[120:123], v[180:183], v[92:95]
	v_mfma_f32_16x16x32_bf16 v[88:91], v[132:135], v[180:183], v[88:91]
	v_mfma_f32_16x16x32_bf16 v[76:79], v[120:123], v[188:191], v[76:79]
	v_mfma_f32_16x16x32_bf16 v[72:75], v[132:135], v[188:191], v[72:75]
	v_mfma_f32_16x16x32_bf16 v[152:155], v[128:131], v[168:171], v[152:155]
	v_mfma_f32_16x16x32_bf16 v[148:151], v[136:139], v[168:171], v[148:151]
	v_mfma_f32_16x16x32_bf16 v[108:111], v[128:131], v[176:179], v[108:111]
	v_mfma_f32_16x16x32_bf16 v[104:107], v[136:139], v[176:179], v[104:107]
	v_mfma_f32_16x16x32_bf16 v[92:95], v[128:131], v[184:187], v[92:95]
	v_mfma_f32_16x16x32_bf16 v[88:91], v[136:139], v[184:187], v[88:91]
	v_mfma_f32_16x16x32_bf16 v[76:79], v[128:131], v[214:217], v[76:79]
	v_mfma_f32_16x16x32_bf16 v[72:75], v[136:139], v[214:217], v[72:75]
	v_mfma_f32_16x16x32_bf16 v[124:127], v[140:143], v[164:167], v[124:127]
	v_mfma_f32_16x16x32_bf16 v[112:115], v[156:159], v[164:167], v[112:115]
	v_mfma_f32_16x16x32_bf16 v[100:103], v[140:143], v[172:175], v[100:103]
	v_mfma_f32_16x16x32_bf16 v[96:99], v[156:159], v[172:175], v[96:99]
	v_mfma_f32_16x16x32_bf16 v[84:87], v[140:143], v[180:183], v[84:87]
	v_mfma_f32_16x16x32_bf16 v[80:83], v[156:159], v[180:183], v[80:83]
	v_mfma_f32_16x16x32_bf16 v[68:71], v[140:143], v[188:191], v[68:71]
	v_mfma_f32_16x16x32_bf16 v[64:67], v[156:159], v[188:191], v[64:67]
	v_mfma_f32_16x16x32_bf16 v[124:127], v[144:147], v[168:171], v[124:127]
	v_mfma_f32_16x16x32_bf16 v[112:115], v[160:163], v[168:171], v[112:115]
	v_mfma_f32_16x16x32_bf16 v[100:103], v[144:147], v[176:179], v[100:103]
	v_mfma_f32_16x16x32_bf16 v[96:99], v[160:163], v[176:179], v[96:99]
	v_mfma_f32_16x16x32_bf16 v[84:87], v[144:147], v[184:187], v[84:87]
	v_mfma_f32_16x16x32_bf16 v[80:83], v[160:163], v[184:187], v[80:83]
	v_mfma_f32_16x16x32_bf16 v[68:71], v[144:147], v[214:217], v[68:71]
	v_mfma_f32_16x16x32_bf16 v[64:67], v[160:163], v[214:217], v[64:67]
	s_barrier
	ds_read_b128 v[164:167], v248 offset:49152
	ds_read_b128 v[168:171], v248 offset:50176
	ds_read_b128 v[172:175], v248 offset:51200
	ds_read_b128 v[176:179], v248 offset:52224
	ds_read_b128 v[180:183], v248 offset:53248
	ds_read_b128 v[184:187], v248 offset:54272
	ds_read_b128 v[188:191], v248 offset:55296
	ds_read_b128 v[214:217], v248 offset:56320
	s_add_u32 s100, s28, 0x80
	s_addc_u32 s101, s29, 0
	s_add_u32 s28, s28, 0x100080
	s_addc_u32 s29, s29, 0
	s_add_u32 s98, s98, 0x80
	s_addc_u32 s99, s99, 0
	s_add_i32 m0, s30, s39
	s_nop 0
	global_load_lds_dwordx4 v194, s[100:101]
	s_add_i32 m0, m0, 0x2000
	s_nop 0
	global_load_lds_dwordx4 v208, s[100:101]
	s_add_i32 m0, s31, s39
	s_nop 0
	global_load_lds_dwordx4 v194, s[28:29]
	s_add_i32 m0, m0, 0x2000
	s_nop 0
	global_load_lds_dwordx4 v208, s[28:29]
	s_mov_b32 m0, s46
	s_nop 0
	global_load_lds_dwordx4 v204, s[98:99]
	s_mov_b32 m0, s48
	s_nop 0
	global_load_lds_dwordx4 v206, s[98:99]
	s_waitcnt vmcnt(8)
	s_waitcnt lgkmcnt(0)
	s_barrier
	v_mfma_f32_16x16x32_bf16 v[60:63], v[120:123], v[164:167], v[60:63]
	v_mfma_f32_16x16x32_bf16 v[56:59], v[132:135], v[164:167], v[56:59]
	v_mfma_f32_16x16x32_bf16 v[44:47], v[120:123], v[172:175], v[44:47]
	v_mfma_f32_16x16x32_bf16 v[40:43], v[132:135], v[172:175], v[40:43]
	v_mfma_f32_16x16x32_bf16 v[28:31], v[120:123], v[180:183], v[28:31]
	v_mfma_f32_16x16x32_bf16 v[24:27], v[132:135], v[180:183], v[24:27]
	v_mfma_f32_16x16x32_bf16 v[12:15], v[120:123], v[188:191], v[12:15]
	v_mfma_f32_16x16x32_bf16 v[8:11], v[132:135], v[188:191], v[8:11]
	v_mfma_f32_16x16x32_bf16 v[60:63], v[128:131], v[168:171], v[60:63]
	v_mfma_f32_16x16x32_bf16 v[56:59], v[136:139], v[168:171], v[56:59]
	v_mfma_f32_16x16x32_bf16 v[44:47], v[128:131], v[176:179], v[44:47]
	v_mfma_f32_16x16x32_bf16 v[40:43], v[136:139], v[176:179], v[40:43]
	v_mfma_f32_16x16x32_bf16 v[28:31], v[128:131], v[184:187], v[28:31]
	v_mfma_f32_16x16x32_bf16 v[24:27], v[136:139], v[184:187], v[24:27]
	v_mfma_f32_16x16x32_bf16 v[12:15], v[128:131], v[214:217], v[12:15]
	v_mfma_f32_16x16x32_bf16 v[8:11], v[136:139], v[214:217], v[8:11]
	v_mfma_f32_16x16x32_bf16 v[52:55], v[140:143], v[164:167], v[52:55]
	v_mfma_f32_16x16x32_bf16 v[48:51], v[156:159], v[164:167], v[48:51]
	v_mfma_f32_16x16x32_bf16 v[36:39], v[140:143], v[172:175], v[36:39]
	v_mfma_f32_16x16x32_bf16 v[32:35], v[156:159], v[172:175], v[32:35]
	v_mfma_f32_16x16x32_bf16 v[20:23], v[140:143], v[180:183], v[20:23]
	v_mfma_f32_16x16x32_bf16 v[16:19], v[156:159], v[180:183], v[16:19]
	v_mfma_f32_16x16x32_bf16 v[4:7], v[140:143], v[188:191], v[4:7]
	v_mfma_f32_16x16x32_bf16 v[0:3], v[156:159], v[188:191], v[0:3]
	v_mfma_f32_16x16x32_bf16 v[52:55], v[144:147], v[168:171], v[52:55]
	v_mfma_f32_16x16x32_bf16 v[48:51], v[160:163], v[168:171], v[48:51]
	v_mfma_f32_16x16x32_bf16 v[36:39], v[144:147], v[176:179], v[36:39]
	v_mfma_f32_16x16x32_bf16 v[32:35], v[160:163], v[176:179], v[32:35]
	v_mfma_f32_16x16x32_bf16 v[20:23], v[144:147], v[184:187], v[20:23]
	v_mfma_f32_16x16x32_bf16 v[16:19], v[160:163], v[184:187], v[16:19]
	v_mfma_f32_16x16x32_bf16 v[4:7], v[144:147], v[214:217], v[4:7]
	v_mfma_f32_16x16x32_bf16 v[0:3], v[160:163], v[214:217], v[0:3]
	s_barrier
	s_add_i32 s56, s56, 2
	s_add_u32 s40, s40, 0x100
	s_addc_u32 s41, s41, 0
	s_cmp_gt_u32 s56, 61
	s_cbranch_scc0 .LBB0_965
	s_and_b64 vcc, exec, s[10:11]
	s_cbranch_vccz .LBB0_968
	s_barrier

; #define PG8_STAGE(bufoff, gbase, voff) do { _Pragma("unroll") for (int _i = 0; _i < 2; ++_i) \
;         __builtin_amdgcn_global_load_lds((const unsigned*)((const char*)(gbase) + (voff)[_i]), (PG8_LAS unsigned*)(lds + (bufoff) + ldsw + _i * 8192), 16, 0, 0); } while (0)
; #define PG8_LDA(dst, b, h) do { _Pragma("unroll") for (int m = 0; m < 4; ++m) _Pragma("unroll") for (int k = 0; k < 2; ++k) dst[m][k] = *(const PG8_LAS bf16x8*)(lds + PG8_SA(b, h) + aoff + m * 2048 + k * 1024); } while (0)
; #define PG8_MMA(ai, bj, At, Bt) do { __builtin_amdgcn_s_setprio(1); _Pragma("unroll") for (int m = 0; m < 4; ++m) _Pragma("unroll") for (int n = 0; n < 2; ++n) _Pragma("unroll") for (int k = 0; k < 2; ++k) \
;         acc[ai][bj][m][n] = __builtin_amdgcn_mfma_f32_16x16x32_bf16(Bt[n][k], At[m][k], acc[ai][bj][m][n], 0, 0, 0); __builtin_amdgcn_s_setprio(0); } while (0)
; #define PG8_WAIT_L(n) asm volatile("s_waitcnt lgkmcnt(" #n ")" ::: "memory")
; #define PG8_WAIT_V8_UNLESS(flag) asm volatile("s_cmp_lg_i32 %0, 0\n\ts_cbranch_scc1 .Lpg8rx%=\n\ts_waitcnt vmcnt(8)\n.Lpg8rx%=:" :: "s"(__builtin_amdgcn_readfirstlane(flag)) : "scc", "memory")
; #define PG8_BAR __builtin_amdgcn_s_barrier()
; #define PG8_SCHED __builtin_amdgcn_sched_barrier(0)
; template <class Epi, class Sched, bool ALIGN_EPI = false, bool SP2 = false>
; __device__ __forceinline__ void gemm_phase(PG8_LAS unsigned char* lds, const Gemm g, const Sched& S, const Epi& E) {
;     ...
;             PG8_WAIT_V8_UNLESS(rx); PG8_WAIT_L(0); PG8_BAR; PG8_MMA(0, 0, At, B0); PG8_MMA(0, 1, At, B1); PG8_BAR; PG8_SCHED;
;             PG8_STAGE(PG8_SB(0, 0), b2, voffB); PG8_STAGE(PG8_SB(0, 1), b2 + hstep, voffB); PG8_STAGE(PG8_SA(0, 0), a2, voffA); PG8_SCHED; PG8_LDA(At, 0, 1);
;             PG8_WAIT_V8_UNLESS(rx); PG8_WAIT_L(0); PG8_BAR; PG8_MMA(1, 0, At, B0); PG8_MMA(1, 1, At, B1); PG8_BAR; PG8_SCHED;
.Lpg8rx8:
	s_waitcnt lgkmcnt(0)
	s_barrier
	v_mfma_f32_16x16x32_bf16 v[120:123], v[140:143], v[172:175], v[120:123]
	v_mfma_f32_16x16x32_bf16 v[124:127], v[148:151], v[172:175], v[124:127]
	v_mfma_f32_16x16x32_bf16 v[108:111], v[140:143], v[180:183], v[108:111]
	v_mfma_f32_16x16x32_bf16 v[104:107], v[148:151], v[180:183], v[104:107]
	v_mfma_f32_16x16x32_bf16 v[92:95], v[140:143], v[188:191], v[92:95]
	v_mfma_f32_16x16x32_bf16 v[88:91], v[148:151], v[188:191], v[88:91]
	v_mfma_f32_16x16x32_bf16 v[76:79], v[140:143], v[208:211], v[76:79]
	v_mfma_f32_16x16x32_bf16 v[72:75], v[148:151], v[208:211], v[72:75]
	v_mfma_f32_16x16x32_bf16 v[120:123], v[144:147], v[176:179], v[120:123]
	v_mfma_f32_16x16x32_bf16 v[124:127], v[152:155], v[176:179], v[124:127]
	v_mfma_f32_16x16x32_bf16 v[108:111], v[144:147], v[184:187], v[108:111]
	v_mfma_f32_16x16x32_bf16 v[104:107], v[152:155], v[184:187], v[104:107]
	v_mfma_f32_16x16x32_bf16 v[92:95], v[144:147], v[204:207], v[92:95]
	v_mfma_f32_16x16x32_bf16 v[88:91], v[152:155], v[204:207], v[88:91]
	v_mfma_f32_16x16x32_bf16 v[76:79], v[144:147], v[212:215], v[76:79]
	v_mfma_f32_16x16x32_bf16 v[72:75], v[152:155], v[212:215], v[72:75]
	v_mfma_f32_16x16x32_bf16 v[116:119], v[156:159], v[172:175], v[116:119]
	v_mfma_f32_16x16x32_bf16 v[112:115], v[164:167], v[172:175], v[112:115]
	v_mfma_f32_16x16x32_bf16 v[100:103], v[156:159], v[180:183], v[100:103]
	v_mfma_f32_16x16x32_bf16 v[96:99], v[164:167], v[180:183], v[96:99]
	v_mfma_f32_16x16x32_bf16 v[84:87], v[156:159], v[188:191], v[84:87]
	v_mfma_f32_16x16x32_bf16 v[80:83], v[164:167], v[188:191], v[80:83]
	v_mfma_f32_16x16x32_bf16 v[68:71], v[156:159], v[208:211], v[68:71]
	v_mfma_f32_16x16x32_bf16 v[64:67], v[164:167], v[208:211], v[64:67]
	v_mfma_f32_16x16x32_bf16 v[116:119], v[160:163], v[176:179], v[116:119]
	v_mfma_f32_16x16x32_bf16 v[112:115], v[168:171], v[176:179], v[112:115]
	v_mfma_f32_16x16x32_bf16 v[100:103], v[160:163], v[184:187], v[100:103]
	v_mfma_f32_16x16x32_bf16 v[96:99], v[168:171], v[184:187], v[96:99]
	v_mfma_f32_16x16x32_bf16 v[84:87], v[160:163], v[204:207], v[84:87]
	v_mfma_f32_16x16x32_bf16 v[80:83], v[168:171], v[204:207], v[80:83]
	v_mfma_f32_16x16x32_bf16 v[68:71], v[160:163], v[212:215], v[68:71]
	v_mfma_f32_16x16x32_bf16 v[64:67], v[168:171], v[212:215], v[64:67]
	s_barrier
	s_add_i32 s63, s63, s34
	v_lshl_add_u64 v[216:217], s[66:67], 0, v[194:195]
	s_mov_b32 m0, s63
	v_lshl_add_u64 v[218:219], s[66:67], 0, v[132:133]
	global_load_lds_dwordx4 v[216:217], off
	s_add_i32 m0, s63, 0x2000
	s_add_u32 s66, s66, s8
	s_addc_u32 s67, s67, s9
	s_add_i32 s63, s65, s34
	global_load_lds_dwordx4 v[218:219], off
	v_lshl_add_u64 v[220:221], s[66:67], 0, v[194:195]
	s_mov_b32 m0, s63
	v_lshl_add_u64 v[222:223], s[66:67], 0, v[132:133]
	global_load_lds_dwordx4 v[220:221], off
	s_add_i32 m0, s63, 0x2000
	v_lshl_add_u64 v[224:225], s[24:25], 0, v[128:129]
	global_load_lds_dwordx4 v[222:223], off
	s_mov_b32 m0, s43
	v_lshl_add_u64 v[226:227], s[24:25], 0, v[130:131]
	global_load_lds_dwordx4 v[224:225], off
	s_mov_b32 m0, s44
	s_nop 0
	global_load_lds_dwordx4 v[226:227], off
	ds_read_b128 v[172:175], v139 offset:16384
	ds_read_b128 v[176:179], v139 offset:17408
	ds_read_b128 v[180:183], v139 offset:18432
	ds_read_b128 v[184:187], v139 offset:19456
	ds_read_b128 v[188:191], v139 offset:20480
	ds_read_b128 v[204:207], v139 offset:21504
	ds_read_b128 v[208:211], v139 offset:22528
	ds_read_b128 v[212:215], v139 offset:23552
	s_cmp_lg_i32 s73, 0
	s_cbranch_scc1 .Lpg8rx9
	s_waitcnt vmcnt(8)
.Lpg8rx9:
	s_waitcnt lgkmcnt(0)
	s_barrier
	v_mfma_f32_16x16x32_bf16 v[60:63], v[140:143], v[172:175], v[60:63]
	v_mfma_f32_16x16x32_bf16 v[56:59], v[148:151], v[172:175], v[56:59]
	v_mfma_f32_16x16x32_bf16 v[44:47], v[140:143], v[180:183], v[44:47]
	v_mfma_f32_16x16x32_bf16 v[40:43], v[148:151], v[180:183], v[40:43]
	v_mfma_f32_16x16x32_bf16 v[28:31], v[140:143], v[188:191], v[28:31]
	v_mfma_f32_16x16x32_bf16 v[24:27], v[148:151], v[188:191], v[24:27]
	v_mfma_f32_16x16x32_bf16 v[12:15], v[140:143], v[208:211], v[12:15]
	v_mfma_f32_16x16x32_bf16 v[8:11], v[148:151], v[208:211], v[8:11]
	v_mfma_f32_16x16x32_bf16 v[60:63], v[144:147], v[176:179], v[60:63]
	v_mfma_f32_16x16x32_bf16 v[56:59], v[152:155], v[176:179], v[56:59]
	v_mfma_f32_16x16x32_bf16 v[44:47], v[144:147], v[184:187], v[44:47]
	v_mfma_f32_16x16x32_bf16 v[40:43], v[152:155], v[184:187], v[40:43]
	v_mfma_f32_16x16x32_bf16 v[28:31], v[144:147], v[204:207], v[28:31]
	v_mfma_f32_16x16x32_bf16 v[24:27], v[152:155], v[204:207], v[24:27]
	v_mfma_f32_16x16x32_bf16 v[12:15], v[144:147], v[212:215], v[12:15]
	v_mfma_f32_16x16x32_bf16 v[8:11], v[152:155], v[212:215], v[8:11]
	v_mfma_f32_16x16x32_bf16 v[52:55], v[156:159], v[172:175], v[52:55]
	v_mfma_f32_16x16x32_bf16 v[48:51], v[164:167], v[172:175], v[48:51]
	v_mfma_f32_16x16x32_bf16 v[36:39], v[156:159], v[180:183], v[36:39]
	v_mfma_f32_16x16x32_bf16 v[32:35], v[164:167], v[180:183], v[32:35]
	v_mfma_f32_16x16x32_bf16 v[20:23], v[156:159], v[188:191], v[20:23]
	v_mfma_f32_16x16x32_bf16 v[16:19], v[164:167], v[188:191], v[16:19]
	v_mfma_f32_16x16x32_bf16 v[4:7], v[156:159], v[208:211], v[4:7]
	v_mfma_f32_16x16x32_bf16 v[0:3], v[164:167], v[208:211], v[0:3]
	v_mfma_f32_16x16x32_bf16 v[52:55], v[160:163], v[176:179], v[52:55]
	v_mfma_f32_16x16x32_bf16 v[48:51], v[168:171], v[176:179], v[48:51]
	v_mfma_f32_16x16x32_bf16 v[36:39], v[160:163], v[184:187], v[36:39]
	v_mfma_f32_16x16x32_bf16 v[32:35], v[168:171], v[184:187], v[32:35]
	v_mfma_f32_16x16x32_bf16 v[20:23], v[160:163], v[204:207], v[20:23]
	v_mfma_f32_16x16x32_bf16 v[16:19], v[168:171], v[204:207], v[16:19]
	v_mfma_f32_16x16x32_bf16 v[4:7], v[160:163], v[212:215], v[4:7]
	v_mfma_f32_16x16x32_bf16 v[0:3], v[168:171], v[212:215], v[0:3]
	s_barrier
; #define PG8_STAGE(bufoff, gbase, voff) do { _Pragma("unroll") for (int _i = 0; _i < 2; ++_i) \
;         __builtin_amdgcn_global_load_lds((const unsigned*)((const char*)(gbase) + (voff)[_i]), (PG8_LAS unsigned*)(lds + (bufoff) + ldsw + _i * 8192), 16, 0, 0); } while (0)
; #define PG8_LDA(dst, b, h) do { _Pragma("unroll") for (int m = 0; m < 4; ++m) _Pragma("unroll") for (int k = 0; k < 2; ++k) dst[m][k] = *(const PG8_LAS bf16x8*)(lds + PG8_SA(b, h) + aoff + m * 2048 + k * 1024); } while (0)
; #define PG8_LDB(dst, b, h) do { _Pragma("unroll") for (int n = 0; n < 2; ++n) _Pragma("unroll") for (int k = 0; k < 2; ++k) dst[n][k] = *(const PG8_LAS bf16x8*)(lds + PG8_SB(b, h) + boff + n * 2048 + k * 1024); } while (0)
; #define PG8_MMA(ai, bj, At, Bt) do { __builtin_amdgcn_s_setprio(1); _Pragma("unroll") for (int m = 0; m < 4; ++m) _Pragma("unroll") for (int n = 0; n < 2; ++n) _Pragma("unroll") for (int k = 0; k < 2; ++k) \
;         acc[ai][bj][m][n] = __builtin_amdgcn_mfma_f32_16x16x32_bf16(Bt[n][k], At[m][k], acc[ai][bj][m][n], 0, 0, 0); __builtin_amdgcn_s_setprio(0); } while (0)
; #define PG8_WAIT_V(n) asm volatile("s_waitcnt vmcnt(" #n ")" ::: "memory")
; #define PG8_WAIT_L(n) asm volatile("s_waitcnt lgkmcnt(" #n ")" ::: "memory")
; #define PG8_BAR __builtin_amdgcn_s_barrier()
; #define PG8_SCHED __builtin_amdgcn_sched_barrier(0)
; template <class Epi, class Sched, bool ALIGN_EPI = false, bool SP2 = false>
; __device__ __forceinline__ void gemm_phase(PG8_LAS unsigned char* lds, const Gemm g, const Sched& S, const Epi& E) {
;     ...
;         for (int t = 0; t < nt; t += 2) {
;     ...
;             PG8_STAGE(PG8_SA(0, 1), a2 + hstep, voffA); PG8_SCHED; PG8_LDB(B0, 1, 0); PG8_LDB(B1, 1, 1); PG8_SCHED; PG8_LDA(At, 1, 0);
;             PG8_WAIT_V(8); PG8_WAIT_L(0); PG8_BAR; PG8_MMA(0, 0, At, B0); PG8_MMA(0, 1, At, B1); PG8_BAR; PG8_SCHED;
;             PG8_STAGE(PG8_SB(1, 0), b3, voffB); PG8_STAGE(PG8_SB(1, 1), b3 + hstep, voffB); PG8_STAGE(PG8_SA(1, 0), a3, voffA); PG8_SCHED; PG8_LDA(At, 1, 1);
;             PG8_WAIT_V(8); PG8_WAIT_L(0); PG8_BAR; PG8_MMA(1, 0, At, B0); PG8_MMA(1, 1, At, B1); PG8_BAR; PG8_SCHED;
	s_add_u32 s24, s24, s8
	s_addc_u32 s25, s25, s9
	s_mov_b32 m0, s46
	v_lshl_add_u64 v[140:141], s[24:25], 0, v[128:129]
	global_load_lds_dwordx4 v[140:141], off
	v_lshl_add_u64 v[140:141], s[24:25], 0, v[130:131]
	s_mov_b32 m0, s48
	s_nop 0
	global_load_lds_dwordx4 v[140:141], off
	s_add_i32 s24, 0, 0x18000
	s_add_i32 s25, 0, 0x1c000
	v_add_u32_e32 v152, s24, v138
	v_add_u32_e32 v168, s25, v138
	ds_read_b128 v[140:143], v152
	ds_read_b128 v[144:147], v152 offset:1024
	ds_read_b128 v[148:151], v152 offset:2048
	ds_read_b128 v[152:155], v152 offset:3072
	ds_read_b128 v[156:159], v168
	ds_read_b128 v[160:163], v168 offset:1024
	ds_read_b128 v[164:167], v168 offset:2048
	ds_read_b128 v[168:171], v168 offset:3072
	ds_read_b128 v[172:175], v139 offset:32768
	ds_read_b128 v[176:179], v139 offset:33792
	ds_read_b128 v[180:183], v139 offset:34816
	ds_read_b128 v[184:187], v139 offset:35840
	ds_read_b128 v[188:191], v139 offset:36864
	ds_read_b128 v[204:207], v139 offset:37888
	ds_read_b128 v[208:211], v139 offset:38912
	ds_read_b128 v[212:215], v139 offset:39936
	s_waitcnt vmcnt(8)
	s_waitcnt lgkmcnt(0)
	s_barrier
	v_mfma_f32_16x16x32_bf16 v[120:123], v[140:143], v[172:175], v[120:123]
	v_mfma_f32_16x16x32_bf16 v[124:127], v[148:151], v[172:175], v[124:127]
	v_mfma_f32_16x16x32_bf16 v[108:111], v[140:143], v[180:183], v[108:111]
	v_mfma_f32_16x16x32_bf16 v[104:107], v[148:151], v[180:183], v[104:107]
	v_mfma_f32_16x16x32_bf16 v[92:95], v[140:143], v[188:191], v[92:95]
	v_mfma_f32_16x16x32_bf16 v[88:91], v[148:151], v[188:191], v[88:91]
	v_mfma_f32_16x16x32_bf16 v[76:79], v[140:143], v[208:211], v[76:79]
	v_mfma_f32_16x16x32_bf16 v[72:75], v[148:151], v[208:211], v[72:75]
	v_mfma_f32_16x16x32_bf16 v[120:123], v[144:147], v[176:179], v[120:123]
	v_mfma_f32_16x16x32_bf16 v[124:127], v[152:155], v[176:179], v[124:127]
	v_mfma_f32_16x16x32_bf16 v[108:111], v[144:147], v[184:187], v[108:111]
	v_mfma_f32_16x16x32_bf16 v[104:107], v[152:155], v[184:187], v[104:107]
	v_mfma_f32_16x16x32_bf16 v[92:95], v[144:147], v[204:207], v[92:95]
	v_mfma_f32_16x16x32_bf16 v[88:91], v[152:155], v[204:207], v[88:91]
	v_mfma_f32_16x16x32_bf16 v[76:79], v[144:147], v[212:215], v[76:79]
	v_mfma_f32_16x16x32_bf16 v[72:75], v[152:155], v[212:215], v[72:75]
	v_mfma_f32_16x16x32_bf16 v[116:119], v[156:159], v[172:175], v[116:119]
	v_mfma_f32_16x16x32_bf16 v[112:115], v[164:167], v[172:175], v[112:115]
	v_mfma_f32_16x16x32_bf16 v[100:103], v[156:159], v[180:183], v[100:103]
	v_mfma_f32_16x16x32_bf16 v[96:99], v[164:167], v[180:183], v[96:99]
	v_mfma_f32_16x16x32_bf16 v[84:87], v[156:159], v[188:191], v[84:87]
	v_mfma_f32_16x16x32_bf16 v[80:83], v[164:167], v[188:191], v[80:83]
	v_mfma_f32_16x16x32_bf16 v[68:71], v[156:159], v[208:211], v[68:71]
	v_mfma_f32_16x16x32_bf16 v[64:67], v[164:167], v[208:211], v[64:67]
	v_mfma_f32_16x16x32_bf16 v[116:119], v[160:163], v[176:179], v[116:119]
	v_mfma_f32_16x16x32_bf16 v[112:115], v[168:171], v[176:179], v[112:115]
	v_mfma_f32_16x16x32_bf16 v[100:103], v[160:163], v[184:187], v[100:103]
	v_mfma_f32_16x16x32_bf16 v[96:99], v[168:171], v[184:187], v[96:99]
	v_mfma_f32_16x16x32_bf16 v[84:87], v[160:163], v[204:207], v[84:87]
	v_mfma_f32_16x16x32_bf16 v[80:83], v[168:171], v[204:207], v[80:83]
	v_mfma_f32_16x16x32_bf16 v[68:71], v[160:163], v[212:215], v[68:71]
	v_mfma_f32_16x16x32_bf16 v[64:67], v[168:171], v[212:215], v[64:67]
	s_barrier
	s_add_i32 s24, s24, s34
	v_lshl_add_u64 v[172:173], v[216:217], 0, s[74:75]
	s_mov_b32 m0, s24
	s_nop 0
	global_load_lds_dwordx4 v[172:173], off
	v_lshl_add_u64 v[172:173], v[218:219], 0, s[74:75]
	s_add_i32 m0, s24, 0x2000
	s_add_i32 s24, s25, s34
	global_load_lds_dwordx4 v[172:173], off
	v_lshl_add_u64 v[172:173], v[220:221], 0, s[74:75]
	s_mov_b32 m0, s24
	s_nop 0
	global_load_lds_dwordx4 v[172:173], off
	v_lshl_add_u64 v[172:173], v[222:223], 0, s[74:75]
	s_add_i32 m0, s24, 0x2000
	s_nop 0
	global_load_lds_dwordx4 v[172:173], off
	v_lshl_add_u64 v[172:173], v[224:225], 0, s[74:75]
	s_mov_b32 m0, s53
	s_nop 0
	global_load_lds_dwordx4 v[172:173], off
	v_lshl_add_u64 v[172:173], v[226:227], 0, s[74:75]
	s_mov_b32 m0, s54
	s_nop 0
	global_load_lds_dwordx4 v[172:173], off
	ds_read_b128 v[172:175], v139 offset:49152
	ds_read_b128 v[176:179], v139 offset:50176
	ds_read_b128 v[180:183], v139 offset:51200
	ds_read_b128 v[184:187], v139 offset:52224
	ds_read_b128 v[188:191], v139 offset:53248
	ds_read_b128 v[204:207], v139 offset:54272
	ds_read_b128 v[208:211], v139 offset:55296
	ds_read_b128 v[212:215], v139 offset:56320
	s_waitcnt vmcnt(8)
	s_waitcnt lgkmcnt(0)
	s_barrier
	v_mfma_f32_16x16x32_bf16 v[60:63], v[140:143], v[172:175], v[60:63]
	v_mfma_f32_16x16x32_bf16 v[56:59], v[148:151], v[172:175], v[56:59]
	v_mfma_f32_16x16x32_bf16 v[44:47], v[140:143], v[180:183], v[44:47]
	v_mfma_f32_16x16x32_bf16 v[40:43], v[148:151], v[180:183], v[40:43]
	v_mfma_f32_16x16x32_bf16 v[28:31], v[140:143], v[188:191], v[28:31]
	v_mfma_f32_16x16x32_bf16 v[24:27], v[148:151], v[188:191], v[24:27]
	v_mfma_f32_16x16x32_bf16 v[12:15], v[140:143], v[208:211], v[12:15]
	v_mfma_f32_16x16x32_bf16 v[8:11], v[148:151], v[208:211], v[8:11]
	v_mfma_f32_16x16x32_bf16 v[60:63], v[144:147], v[176:179], v[60:63]
	v_mfma_f32_16x16x32_bf16 v[56:59], v[152:155], v[176:179], v[56:59]
	v_mfma_f32_16x16x32_bf16 v[44:47], v[144:147], v[184:187], v[44:47]
	v_mfma_f32_16x16x32_bf16 v[40:43], v[152:155], v[184:187], v[40:43]
	v_mfma_f32_16x16x32_bf16 v[28:31], v[144:147], v[204:207], v[28:31]
	v_mfma_f32_16x16x32_bf16 v[24:27], v[152:155], v[204:207], v[24:27]
	v_mfma_f32_16x16x32_bf16 v[12:15], v[144:147], v[212:215], v[12:15]
	v_mfma_f32_16x16x32_bf16 v[8:11], v[152:155], v[212:215], v[8:11]
	v_mfma_f32_16x16x32_bf16 v[52:55], v[156:159], v[172:175], v[52:55]
	v_mfma_f32_16x16x32_bf16 v[48:51], v[164:167], v[172:175], v[48:51]
	v_mfma_f32_16x16x32_bf16 v[36:39], v[156:159], v[180:183], v[36:39]
	v_mfma_f32_16x16x32_bf16 v[32:35], v[164:167], v[180:183], v[32:35]
	v_mfma_f32_16x16x32_bf16 v[20:23], v[156:159], v[188:191], v[20:23]
	v_mfma_f32_16x16x32_bf16 v[16:19], v[164:167], v[188:191], v[16:19]
	v_mfma_f32_16x16x32_bf16 v[4:7], v[156:159], v[208:211], v[4:7]
	v_mfma_f32_16x16x32_bf16 v[0:3], v[164:167], v[208:211], v[0:3]
	v_mfma_f32_16x16x32_bf16 v[52:55], v[160:163], v[176:179], v[52:55]
	v_mfma_f32_16x16x32_bf16 v[48:51], v[168:171], v[176:179], v[48:51]
	v_mfma_f32_16x16x32_bf16 v[36:39], v[160:163], v[184:187], v[36:39]
	v_mfma_f32_16x16x32_bf16 v[32:35], v[168:171], v[184:187], v[32:35]
	v_mfma_f32_16x16x32_bf16 v[20:23], v[160:163], v[204:207], v[20:23]
	v_mfma_f32_16x16x32_bf16 v[16:19], v[168:171], v[204:207], v[16:19]
	v_mfma_f32_16x16x32_bf16 v[4:7], v[160:163], v[212:215], v[4:7]
	v_mfma_f32_16x16x32_bf16 v[0:3], v[168:171], v[212:215], v[0:3]
	s_barrier
	s_add_u32 s22, s22, 0x100
	s_addc_u32 s23, s23, 0
	s_add_u32 s60, s60, 0x100
	s_addc_u32 s61, s61, 0
	s_cmp_ge_i32 s62, s51
	s_mov_b32 s24, s62
	s_cbranch_scc0 .LBB0_1091

; #define PG8_STAGE(bufoff, gbase, voff) do { _Pragma("unroll") for (int _i = 0; _i < 2; ++_i) \
;         __builtin_amdgcn_global_load_lds((const unsigned*)((const char*)(gbase) + (voff)[_i]), (PG8_LAS unsigned*)(lds + (bufoff) + ldsw + _i * 8192), 16, 0, 0); } while (0)
; #define PG8_LDA(dst, b, h) do { _Pragma("unroll") for (int m = 0; m < 4; ++m) _Pragma("unroll") for (int k = 0; k < 2; ++k) dst[m][k] = *(const PG8_LAS bf16x8*)(lds + PG8_SA(b, h) + aoff + m * 2048 + k * 1024); } while (0)
; #define PG8_MMA(ai, bj, At, Bt) do { __builtin_amdgcn_s_setprio(1); _Pragma("unroll") for (int m = 0; m < 4; ++m) _Pragma("unroll") for (int n = 0; n < 2; ++n) _Pragma("unroll") for (int k = 0; k < 2; ++k) \
;         acc[ai][bj][m][n] = __builtin_amdgcn_mfma_f32_16x16x32_bf16(Bt[n][k], At[m][k], acc[ai][bj][m][n], 0, 0, 0); __builtin_amdgcn_s_setprio(0); } while (0)
; #define PG8_WAIT_L(n) asm volatile("s_waitcnt lgkmcnt(" #n ")" ::: "memory")
; #define PG8_WAIT_V8_UNLESS(flag) asm volatile("s_cmp_lg_i32 %0, 0\n\ts_cbranch_scc1 .Lpg8rx%=\n\ts_waitcnt vmcnt(8)\n.Lpg8rx%=:" :: "s"(__builtin_amdgcn_readfirstlane(flag)) : "scc", "memory")
; #define PG8_BAR __builtin_amdgcn_s_barrier()
; #define PG8_SCHED __builtin_amdgcn_sched_barrier(0)
; template <class Epi, class Sched, bool ALIGN_EPI = false, bool SP2 = false>
; __device__ __forceinline__ void gemm_phase(PG8_LAS unsigned char* lds, const Gemm g, const Sched& S, const Epi& E) {
;     ...
;             PG8_WAIT_V8_UNLESS(rx); PG8_WAIT_L(0); PG8_BAR; PG8_MMA(0, 0, At, B0); PG8_MMA(0, 1, At, B1); PG8_BAR; PG8_SCHED;
;             PG8_STAGE(PG8_SB(0, 0), b2, voffB); PG8_STAGE(PG8_SB(0, 1), b2 + hstep, voffB); PG8_STAGE(PG8_SA(0, 0), a2, voffA); PG8_SCHED; PG8_LDA(At, 0, 1);
;             PG8_WAIT_V8_UNLESS(rx); PG8_WAIT_L(0); PG8_BAR; PG8_MMA(1, 0, At, B0); PG8_MMA(1, 1, At, B1); PG8_BAR; PG8_SCHED;
.Lpg8rx10:
	s_waitcnt lgkmcnt(0)
	s_barrier
	v_mfma_f32_16x16x32_bf16 v[124:127], v[132:135], v[180:183], v[124:127]
	v_mfma_f32_16x16x32_bf16 v[120:123], v[140:143], v[180:183], v[120:123]
	v_mfma_f32_16x16x32_bf16 v[108:111], v[132:135], v[188:191], v[108:111]
	v_mfma_f32_16x16x32_bf16 v[104:107], v[140:143], v[188:191], v[104:107]
	v_mfma_f32_16x16x32_bf16 v[92:95], v[132:135], v[208:211], v[92:95]
	v_mfma_f32_16x16x32_bf16 v[88:91], v[140:143], v[208:211], v[88:91]
	v_mfma_f32_16x16x32_bf16 v[76:79], v[132:135], v[216:219], v[76:79]
	v_mfma_f32_16x16x32_bf16 v[72:75], v[140:143], v[216:219], v[72:75]
	v_mfma_f32_16x16x32_bf16 v[124:127], v[136:139], v[184:187], v[124:127]
	v_mfma_f32_16x16x32_bf16 v[120:123], v[144:147], v[184:187], v[120:123]
	v_mfma_f32_16x16x32_bf16 v[108:111], v[136:139], v[204:207], v[108:111]
	v_mfma_f32_16x16x32_bf16 v[104:107], v[144:147], v[204:207], v[104:107]
	v_mfma_f32_16x16x32_bf16 v[92:95], v[136:139], v[212:215], v[92:95]
	v_mfma_f32_16x16x32_bf16 v[88:91], v[144:147], v[212:215], v[88:91]
	v_mfma_f32_16x16x32_bf16 v[76:79], v[136:139], v[220:223], v[76:79]
	v_mfma_f32_16x16x32_bf16 v[72:75], v[144:147], v[220:223], v[72:75]
	v_mfma_f32_16x16x32_bf16 v[116:119], v[160:163], v[180:183], v[116:119]
	v_mfma_f32_16x16x32_bf16 v[112:115], v[168:171], v[180:183], v[112:115]
	v_mfma_f32_16x16x32_bf16 v[100:103], v[160:163], v[188:191], v[100:103]
	v_mfma_f32_16x16x32_bf16 v[96:99], v[168:171], v[188:191], v[96:99]
	v_mfma_f32_16x16x32_bf16 v[84:87], v[160:163], v[208:211], v[84:87]
	v_mfma_f32_16x16x32_bf16 v[80:83], v[168:171], v[208:211], v[80:83]
	v_mfma_f32_16x16x32_bf16 v[68:71], v[160:163], v[216:219], v[68:71]
	v_mfma_f32_16x16x32_bf16 v[64:67], v[168:171], v[216:219], v[64:67]
	v_mfma_f32_16x16x32_bf16 v[116:119], v[164:167], v[184:187], v[116:119]
	v_mfma_f32_16x16x32_bf16 v[112:115], v[176:179], v[184:187], v[112:115]
	v_mfma_f32_16x16x32_bf16 v[100:103], v[164:167], v[204:207], v[100:103]
	v_mfma_f32_16x16x32_bf16 v[96:99], v[176:179], v[204:207], v[96:99]
	v_mfma_f32_16x16x32_bf16 v[84:87], v[164:167], v[212:215], v[84:87]
	v_mfma_f32_16x16x32_bf16 v[80:83], v[176:179], v[212:215], v[80:83]
	v_mfma_f32_16x16x32_bf16 v[68:71], v[164:167], v[220:223], v[68:71]
	v_mfma_f32_16x16x32_bf16 v[64:67], v[176:179], v[220:223], v[64:67]
	s_barrier
	ds_read_b128 v[180:183], v175 offset:16384
	ds_read_b128 v[184:187], v175 offset:17408
	ds_read_b128 v[188:191], v175 offset:18432
	ds_read_b128 v[204:207], v175 offset:19456
	ds_read_b128 v[208:211], v175 offset:20480
	ds_read_b128 v[212:215], v175 offset:21504
	ds_read_b128 v[216:219], v175 offset:22528
	ds_read_b128 v[220:223], v175 offset:23552
	s_add_u32 s60, s28, 0x40000
	s_addc_u32 s61, s29, 0
	s_add_i32 m0, s65, s35
	s_nop 0
	global_load_lds_dwordx4 v150, s[28:29]
	s_add_i32 m0, m0, 0x2000
	s_nop 0
	global_load_lds_dwordx4 v154, s[28:29]
	s_add_i32 m0, s66, s35
	s_nop 0
	global_load_lds_dwordx4 v150, s[60:61]
	s_add_i32 m0, m0, 0x2000
	s_nop 0
	global_load_lds_dwordx4 v154, s[60:61]
	s_mov_b32 m0, s41
	s_nop 0
	global_load_lds_dwordx4 v148, s[30:31]
	s_mov_b32 m0, s48
	s_nop 0
	global_load_lds_dwordx4 v152, s[30:31]
	s_cmp_lg_i32 s67, 0
	s_cbranch_scc1 .Lpg8rx11
	s_waitcnt vmcnt(8)
.Lpg8rx11:
	s_waitcnt lgkmcnt(0)
	s_barrier
	v_mfma_f32_16x16x32_bf16 v[60:63], v[132:135], v[180:183], v[60:63]
	v_mfma_f32_16x16x32_bf16 v[56:59], v[140:143], v[180:183], v[56:59]
	v_mfma_f32_16x16x32_bf16 v[44:47], v[132:135], v[188:191], v[44:47]
	v_mfma_f32_16x16x32_bf16 v[40:43], v[140:143], v[188:191], v[40:43]
	v_mfma_f32_16x16x32_bf16 v[28:31], v[132:135], v[208:211], v[28:31]
	v_mfma_f32_16x16x32_bf16 v[24:27], v[140:143], v[208:211], v[24:27]
	v_mfma_f32_16x16x32_bf16 v[12:15], v[132:135], v[216:219], v[12:15]
	v_mfma_f32_16x16x32_bf16 v[8:11], v[140:143], v[216:219], v[8:11]
	v_mfma_f32_16x16x32_bf16 v[60:63], v[136:139], v[184:187], v[60:63]
	v_mfma_f32_16x16x32_bf16 v[56:59], v[144:147], v[184:187], v[56:59]
	v_mfma_f32_16x16x32_bf16 v[44:47], v[136:139], v[204:207], v[44:47]
	v_mfma_f32_16x16x32_bf16 v[40:43], v[144:147], v[204:207], v[40:43]
	v_mfma_f32_16x16x32_bf16 v[28:31], v[136:139], v[212:215], v[28:31]
	v_mfma_f32_16x16x32_bf16 v[24:27], v[144:147], v[212:215], v[24:27]
	v_mfma_f32_16x16x32_bf16 v[12:15], v[136:139], v[220:223], v[12:15]
	v_mfma_f32_16x16x32_bf16 v[8:11], v[144:147], v[220:223], v[8:11]
	v_mfma_f32_16x16x32_bf16 v[52:55], v[160:163], v[180:183], v[52:55]
	v_mfma_f32_16x16x32_bf16 v[48:51], v[168:171], v[180:183], v[48:51]
	v_mfma_f32_16x16x32_bf16 v[36:39], v[160:163], v[188:191], v[36:39]
	v_mfma_f32_16x16x32_bf16 v[32:35], v[168:171], v[188:191], v[32:35]
	v_mfma_f32_16x16x32_bf16 v[20:23], v[160:163], v[208:211], v[20:23]
	v_mfma_f32_16x16x32_bf16 v[16:19], v[168:171], v[208:211], v[16:19]
	v_mfma_f32_16x16x32_bf16 v[4:7], v[160:163], v[216:219], v[4:7]
	v_mfma_f32_16x16x32_bf16 v[0:3], v[168:171], v[216:219], v[0:3]
	v_mfma_f32_16x16x32_bf16 v[52:55], v[164:167], v[184:187], v[52:55]
	v_mfma_f32_16x16x32_bf16 v[48:51], v[176:179], v[184:187], v[48:51]
	v_mfma_f32_16x16x32_bf16 v[36:39], v[164:167], v[204:207], v[36:39]
	v_mfma_f32_16x16x32_bf16 v[32:35], v[176:179], v[204:207], v[32:35]
	v_mfma_f32_16x16x32_bf16 v[20:23], v[164:167], v[212:215], v[20:23]
	v_mfma_f32_16x16x32_bf16 v[16:19], v[176:179], v[212:215], v[16:19]
	v_mfma_f32_16x16x32_bf16 v[4:7], v[164:167], v[220:223], v[4:7]
	v_mfma_f32_16x16x32_bf16 v[0:3], v[176:179], v[220:223], v[0:3]
	s_barrier
; #define PG8_STAGE(bufoff, gbase, voff) do { _Pragma("unroll") for (int _i = 0; _i < 2; ++_i) \
;         __builtin_amdgcn_global_load_lds((const unsigned*)((const char*)(gbase) + (voff)[_i]), (PG8_LAS unsigned*)(lds + (bufoff) + ldsw + _i * 8192), 16, 0, 0); } while (0)
; #define PG8_LDA(dst, b, h) do { _Pragma("unroll") for (int m = 0; m < 4; ++m) _Pragma("unroll") for (int k = 0; k < 2; ++k) dst[m][k] = *(const PG8_LAS bf16x8*)(lds + PG8_SA(b, h) + aoff + m * 2048 + k * 1024); } while (0)
; #define PG8_LDB(dst, b, h) do { _Pragma("unroll") for (int n = 0; n < 2; ++n) _Pragma("unroll") for (int k = 0; k < 2; ++k) dst[n][k] = *(const PG8_LAS bf16x8*)(lds + PG8_SB(b, h) + boff + n * 2048 + k * 1024); } while (0)
; #define PG8_MMA(ai, bj, At, Bt) do { __builtin_amdgcn_s_setprio(1); _Pragma("unroll") for (int m = 0; m < 4; ++m) _Pragma("unroll") for (int n = 0; n < 2; ++n) _Pragma("unroll") for (int k = 0; k < 2; ++k) \
;         acc[ai][bj][m][n] = __builtin_amdgcn_mfma_f32_16x16x32_bf16(Bt[n][k], At[m][k], acc[ai][bj][m][n], 0, 0, 0); __builtin_amdgcn_s_setprio(0); } while (0)
; #define PG8_WAIT_V(n) asm volatile("s_waitcnt vmcnt(" #n ")" ::: "memory")
; #define PG8_WAIT_L(n) asm volatile("s_waitcnt lgkmcnt(" #n ")" ::: "memory")
; #define PG8_BAR __builtin_amdgcn_s_barrier()
; #define PG8_SCHED __builtin_amdgcn_sched_barrier(0)
; template <class Epi, class Sched, bool ALIGN_EPI = false, bool SP2 = false>
; __device__ __forceinline__ void gemm_phase(PG8_LAS unsigned char* lds, const Gemm g, const Sched& S, const Epi& E) {
;     ...
;         for (int t = 0; t < nt; t += 2) {
;     ...
;             PG8_STAGE(PG8_SA(0, 1), a2 + hstep, voffA); PG8_SCHED; PG8_LDB(B0, 1, 0); PG8_LDB(B1, 1, 1); PG8_SCHED; PG8_LDA(At, 1, 0);
;             PG8_WAIT_V(8); PG8_WAIT_L(0); PG8_BAR; PG8_MMA(0, 0, At, B0); PG8_MMA(0, 1, At, B1); PG8_BAR; PG8_SCHED;
;             PG8_STAGE(PG8_SB(1, 0), b3, voffB); PG8_STAGE(PG8_SB(1, 1), b3 + hstep, voffB); PG8_STAGE(PG8_SA(1, 0), a3, voffA); PG8_SCHED; PG8_LDA(At, 1, 1);
;             PG8_WAIT_V(8); PG8_WAIT_L(0); PG8_BAR; PG8_MMA(1, 0, At, B0); PG8_MMA(1, 1, At, B1); PG8_BAR; PG8_SCHED;
	s_mov_b64 s[98:99], s[30:31]
	s_add_u32 s100, s30, 0x40000
	s_addc_u32 s101, s31, 0
	s_add_i32 s30, 0, 0x18000
	s_add_i32 s31, 0, 0x1c000
	v_add_u32_e32 v144, s30, v174
	v_add_u32_e32 v176, s31, v174
	ds_read_b128 v[132:135], v144
	ds_read_b128 v[136:139], v144 offset:1024
	ds_read_b128 v[140:143], v144 offset:2048
	ds_read_b128 v[144:147], v144 offset:3072
	ds_read_b128 v[160:163], v176
	ds_read_b128 v[164:167], v176 offset:1024
	ds_read_b128 v[168:171], v176 offset:2048
	ds_read_b128 v[176:179], v176 offset:3072
	ds_read_b128 v[180:183], v175 offset:32768
	ds_read_b128 v[184:187], v175 offset:33792
	ds_read_b128 v[188:191], v175 offset:34816
	ds_read_b128 v[204:207], v175 offset:35840
	ds_read_b128 v[208:211], v175 offset:36864
	ds_read_b128 v[212:215], v175 offset:37888
	ds_read_b128 v[216:219], v175 offset:38912
	ds_read_b128 v[220:223], v175 offset:39936
	s_mov_b32 m0, s50
	s_nop 0
	global_load_lds_dwordx4 v148, s[100:101]
	s_mov_b32 m0, s51
	s_nop 0
	global_load_lds_dwordx4 v152, s[100:101]
	s_waitcnt vmcnt(8)
	s_waitcnt lgkmcnt(0)
	s_barrier
	v_mfma_f32_16x16x32_bf16 v[124:127], v[132:135], v[180:183], v[124:127]
	v_mfma_f32_16x16x32_bf16 v[120:123], v[140:143], v[180:183], v[120:123]
	v_mfma_f32_16x16x32_bf16 v[108:111], v[132:135], v[188:191], v[108:111]
	v_mfma_f32_16x16x32_bf16 v[104:107], v[140:143], v[188:191], v[104:107]
	v_mfma_f32_16x16x32_bf16 v[92:95], v[132:135], v[208:211], v[92:95]
	v_mfma_f32_16x16x32_bf16 v[88:91], v[140:143], v[208:211], v[88:91]
	v_mfma_f32_16x16x32_bf16 v[76:79], v[132:135], v[216:219], v[76:79]
	v_mfma_f32_16x16x32_bf16 v[72:75], v[140:143], v[216:219], v[72:75]
	v_mfma_f32_16x16x32_bf16 v[124:127], v[136:139], v[184:187], v[124:127]
	v_mfma_f32_16x16x32_bf16 v[120:123], v[144:147], v[184:187], v[120:123]
	v_mfma_f32_16x16x32_bf16 v[108:111], v[136:139], v[204:207], v[108:111]
	v_mfma_f32_16x16x32_bf16 v[104:107], v[144:147], v[204:207], v[104:107]
	v_mfma_f32_16x16x32_bf16 v[92:95], v[136:139], v[212:215], v[92:95]
	v_mfma_f32_16x16x32_bf16 v[88:91], v[144:147], v[212:215], v[88:91]
	v_mfma_f32_16x16x32_bf16 v[76:79], v[136:139], v[220:223], v[76:79]
	v_mfma_f32_16x16x32_bf16 v[72:75], v[144:147], v[220:223], v[72:75]
	v_mfma_f32_16x16x32_bf16 v[116:119], v[160:163], v[180:183], v[116:119]
	v_mfma_f32_16x16x32_bf16 v[112:115], v[168:171], v[180:183], v[112:115]
	v_mfma_f32_16x16x32_bf16 v[100:103], v[160:163], v[188:191], v[100:103]
	v_mfma_f32_16x16x32_bf16 v[96:99], v[168:171], v[188:191], v[96:99]
	v_mfma_f32_16x16x32_bf16 v[84:87], v[160:163], v[208:211], v[84:87]
	v_mfma_f32_16x16x32_bf16 v[80:83], v[168:171], v[208:211], v[80:83]
	v_mfma_f32_16x16x32_bf16 v[68:71], v[160:163], v[216:219], v[68:71]
	v_mfma_f32_16x16x32_bf16 v[64:67], v[168:171], v[216:219], v[64:67]
	v_mfma_f32_16x16x32_bf16 v[116:119], v[164:167], v[184:187], v[116:119]
	v_mfma_f32_16x16x32_bf16 v[112:115], v[176:179], v[184:187], v[112:115]
	v_mfma_f32_16x16x32_bf16 v[100:103], v[164:167], v[204:207], v[100:103]
	v_mfma_f32_16x16x32_bf16 v[96:99], v[176:179], v[204:207], v[96:99]
	v_mfma_f32_16x16x32_bf16 v[84:87], v[164:167], v[212:215], v[84:87]
	v_mfma_f32_16x16x32_bf16 v[80:83], v[176:179], v[212:215], v[80:83]
	v_mfma_f32_16x16x32_bf16 v[68:71], v[164:167], v[220:223], v[68:71]
	v_mfma_f32_16x16x32_bf16 v[64:67], v[176:179], v[220:223], v[64:67]
	s_barrier
	ds_read_b128 v[180:183], v175 offset:49152
	ds_read_b128 v[184:187], v175 offset:50176
	ds_read_b128 v[188:191], v175 offset:51200
	ds_read_b128 v[204:207], v175 offset:52224
	ds_read_b128 v[208:211], v175 offset:53248
	ds_read_b128 v[212:215], v175 offset:54272
	ds_read_b128 v[216:219], v175 offset:55296
	ds_read_b128 v[220:223], v175 offset:56320
	s_add_u32 s100, s28, 0x80
	s_addc_u32 s101, s29, 0
	s_add_u32 s28, s28, 0x40080
	s_addc_u32 s29, s29, 0
	s_add_u32 s98, s98, 0x80
	s_addc_u32 s99, s99, 0
	s_add_i32 m0, s30, s35
	s_nop 0
	global_load_lds_dwordx4 v150, s[100:101]
	s_add_i32 m0, m0, 0x2000
	s_nop 0
	global_load_lds_dwordx4 v154, s[100:101]
	s_add_i32 m0, s31, s35
	s_nop 0
	global_load_lds_dwordx4 v150, s[28:29]
	s_add_i32 m0, m0, 0x2000
	s_nop 0
	global_load_lds_dwordx4 v154, s[28:29]
	s_mov_b32 m0, s52
	s_nop 0
	global_load_lds_dwordx4 v148, s[98:99]
	s_mov_b32 m0, s53
	s_nop 0
	global_load_lds_dwordx4 v152, s[98:99]
	s_waitcnt vmcnt(8)
	s_waitcnt lgkmcnt(0)
	s_barrier
	v_mfma_f32_16x16x32_bf16 v[60:63], v[132:135], v[180:183], v[60:63]
	v_mfma_f32_16x16x32_bf16 v[56:59], v[140:143], v[180:183], v[56:59]
	v_mfma_f32_16x16x32_bf16 v[44:47], v[132:135], v[188:191], v[44:47]
	v_mfma_f32_16x16x32_bf16 v[40:43], v[140:143], v[188:191], v[40:43]
	v_mfma_f32_16x16x32_bf16 v[28:31], v[132:135], v[208:211], v[28:31]
	v_mfma_f32_16x16x32_bf16 v[24:27], v[140:143], v[208:211], v[24:27]
	v_mfma_f32_16x16x32_bf16 v[12:15], v[132:135], v[216:219], v[12:15]
	v_mfma_f32_16x16x32_bf16 v[8:11], v[140:143], v[216:219], v[8:11]
	v_mfma_f32_16x16x32_bf16 v[60:63], v[136:139], v[184:187], v[60:63]
	v_mfma_f32_16x16x32_bf16 v[56:59], v[144:147], v[184:187], v[56:59]
	v_mfma_f32_16x16x32_bf16 v[44:47], v[136:139], v[204:207], v[44:47]
	v_mfma_f32_16x16x32_bf16 v[40:43], v[144:147], v[204:207], v[40:43]
	v_mfma_f32_16x16x32_bf16 v[28:31], v[136:139], v[212:215], v[28:31]
	v_mfma_f32_16x16x32_bf16 v[24:27], v[144:147], v[212:215], v[24:27]
	v_mfma_f32_16x16x32_bf16 v[12:15], v[136:139], v[220:223], v[12:15]
	v_mfma_f32_16x16x32_bf16 v[8:11], v[144:147], v[220:223], v[8:11]
	v_mfma_f32_16x16x32_bf16 v[52:55], v[160:163], v[180:183], v[52:55]
	v_mfma_f32_16x16x32_bf16 v[48:51], v[168:171], v[180:183], v[48:51]
	v_mfma_f32_16x16x32_bf16 v[36:39], v[160:163], v[188:191], v[36:39]
	v_mfma_f32_16x16x32_bf16 v[32:35], v[168:171], v[188:191], v[32:35]
	v_mfma_f32_16x16x32_bf16 v[20:23], v[160:163], v[208:211], v[20:23]
	v_mfma_f32_16x16x32_bf16 v[16:19], v[168:171], v[208:211], v[16:19]
	v_mfma_f32_16x16x32_bf16 v[4:7], v[160:163], v[216:219], v[4:7]
	v_mfma_f32_16x16x32_bf16 v[0:3], v[168:171], v[216:219], v[0:3]
	v_mfma_f32_16x16x32_bf16 v[52:55], v[164:167], v[184:187], v[52:55]
	v_mfma_f32_16x16x32_bf16 v[48:51], v[176:179], v[184:187], v[48:51]
	v_mfma_f32_16x16x32_bf16 v[36:39], v[164:167], v[204:207], v[36:39]
	v_mfma_f32_16x16x32_bf16 v[32:35], v[176:179], v[204:207], v[32:35]
	v_mfma_f32_16x16x32_bf16 v[20:23], v[164:167], v[212:215], v[20:23]
	v_mfma_f32_16x16x32_bf16 v[16:19], v[176:179], v[212:215], v[16:19]
	v_mfma_f32_16x16x32_bf16 v[4:7], v[164:167], v[220:223], v[4:7]
	v_mfma_f32_16x16x32_bf16 v[0:3], v[176:179], v[220:223], v[0:3]
	s_barrier
	s_add_i32 s59, s59, 2
	s_add_u32 vcc_lo, vcc_lo, 0x100
	s_addc_u32 vcc_hi, vcc_hi, 0
	s_cmp_gt_u32 s59, 13
	s_cbranch_scc0 .LBB0_1133
	s_and_b64 vcc, exec, s[14:15]
	s_cbranch_vccz .LBB0_1136
	s_barrier
